# adds conv_w: counted vmcnt at loop head (6 loops) and deferred load wait/select in the ride-along loop
# baseline (speedup 1.0000x reference)
; #define LAUNDER_V(x) asm volatile("" : "+v"(x))
; #define LAUNDER_S(x) asm volatile("" : "+s"(x))
;     float* tile = (float*)ldsb;
;     int tid = threadIdx.x; LAUNDER_V(tid); int bid = blockIdx.x; LAUNDER_S(bid);
;     const int nkt = K / 64, ntiles = (Ntot / 128) * nkt;
;     float v[16];
;     ...
;     const int cstride = nwg ? nwg : (int)gridDim.x; bid -= wg0;
;     if (bid < 0) return;
;     if (bid < ntiles) CONVW_LOAD(bid);
.LBB0_11:
	v_readlane_b32 s8, v253, 0
	v_readlane_b32 s22, v253, 14
	v_readlane_b32 s23, v253, 15
	s_mov_b64 s[0:1], s[22:23]
	s_add_u32 s6, s0, 0x17000000
	s_addc_u32 s7, s1, 0
	s_sub_i32 s3, s34, 32
	v_readlane_b32 s12, v253, 4
	v_mov_b32_e32 v1, v192
	s_mov_b32 s8, s52
	s_cmp_lg_u32 s3, 0
	v_readlane_b32 s10, v253, 2
	s_cselect_b32 s3, s3, 32
	s_sub_i32 s12, s8, 32
	s_cmpk_gt_u32 s12, 0x15f
	s_mul_i32 s10, s3, 0x2c000
	v_readlane_b32 s9, v253, 1
	v_readlane_b32 s11, v253, 3
	v_readlane_b32 s13, v253, 5
	v_readlane_b32 s14, v253, 6
	v_readlane_b32 s15, v253, 7
	v_readlane_b32 s16, v253, 8
	v_readlane_b32 s17, v253, 9
	v_readlane_b32 s18, v253, 10
	v_readlane_b32 s19, v253, 11
	v_readlane_b32 s20, v253, 12
	v_readlane_b32 s21, v253, 13
	s_cbranch_scc1 .LBB0_16
	s_lshl_b32 s9, s12, 3
	s_and_b32 s9, s9, 0xf80
	s_lshl_b32 s8, s8, 6
	v_and_b32_e32 v17, 0x7f, v1
	s_and_b32 s8, s8, 0x3c0
	v_or_b32_e32 v2, s9, v17
	v_ashrrev_i32_e32 v16, 7, v1
	v_add_u32_e32 v25, 0x200, v1
	v_lshlrev_b32_e32 v18, 2, v2
	v_mov_b32_e32 v19, 0
	v_add_u32_e32 v4, s8, v16
	s_movk_i32 s11, 0xb00
	v_ashrrev_i32_e32 v75, 7, v25
	v_add_u32_e32 v28, 0x400, v1
	v_lshl_add_u64 v[2:3], s[70:71], 0, v[18:19]
	v_mul_lo_u32 v18, v4, s11
	v_add_u32_e32 v6, s8, v75
	v_ashrrev_i32_e32 v74, 7, v28
	v_add_u32_e32 v31, 0x600, v1
	v_lshl_add_u64 v[4:5], v[18:19], 2, v[2:3]
	v_mul_lo_u32 v18, v6, s11
	v_add_u32_e32 v8, s8, v74
	v_ashrrev_i32_e32 v73, 7, v31
	v_add_u32_e32 v34, 0x800, v1
	v_lshl_add_u64 v[6:7], v[18:19], 2, v[2:3]
	v_mul_lo_u32 v18, v8, s11
	v_add_u32_e32 v10, s8, v73
	v_ashrrev_i32_e32 v72, 7, v34
	v_add_u32_e32 v37, 0xa00, v1
	v_lshl_add_u64 v[8:9], v[18:19], 2, v[2:3]
	v_mul_lo_u32 v18, v10, s11
	v_add_u32_e32 v12, s8, v72
	v_ashrrev_i32_e32 v71, 7, v37
	v_lshl_add_u64 v[10:11], v[18:19], 2, v[2:3]
	v_mul_lo_u32 v18, v12, s11
	v_add_u32_e32 v14, s8, v71
	v_add_u32_e32 v40, 0xc00, v1
	v_lshl_add_u64 v[12:13], v[18:19], 2, v[2:3]
	v_mul_lo_u32 v18, v14, s11
	v_ashrrev_i32_e32 v70, 7, v40
	v_lshl_add_u64 v[14:15], v[18:19], 2, v[2:3]
	v_add_u32_e32 v18, s8, v70
	v_add_u32_e32 v59, 0xe00, v1
	v_mul_lo_u32 v18, v18, s11
	v_ashrrev_i32_e32 v69, 7, v59
	v_lshl_add_u64 v[78:79], v[18:19], 2, v[2:3]
	v_add_u32_e32 v18, s8, v69
	v_mul_lo_u32 v18, v18, s11
	v_lshl_add_u64 v[80:81], v[18:19], 2, v[2:3]
	v_add_u32_e32 v18, 0x1000, v1
	v_ashrrev_i32_e32 v68, 7, v18
	v_add_u32_e32 v18, s8, v68
	v_mul_lo_u32 v18, v18, s11
	v_lshl_add_u64 v[82:83], v[18:19], 2, v[2:3]
	v_add_u32_e32 v18, 0x1200, v1
	v_ashrrev_i32_e32 v67, 7, v18
	v_add_u32_e32 v18, s8, v67
	v_mul_lo_u32 v18, v18, s11
	v_lshl_add_u64 v[84:85], v[18:19], 2, v[2:3]
	v_add_u32_e32 v18, 0x1400, v1
	v_ashrrev_i32_e32 v66, 7, v18
	v_add_u32_e32 v18, s8, v66
	v_mul_lo_u32 v18, v18, s11
	v_lshl_add_u64 v[86:87], v[18:19], 2, v[2:3]
	v_add_u32_e32 v18, 0x1600, v1
	v_ashrrev_i32_e32 v65, 7, v18
	v_add_u32_e32 v18, s8, v65
	v_mul_lo_u32 v18, v18, s11
	v_lshl_add_u64 v[88:89], v[18:19], 2, v[2:3]
	v_add_u32_e32 v18, 0x1800, v1
	v_ashrrev_i32_e32 v64, 7, v18
	v_add_u32_e32 v18, s8, v64
	v_mul_lo_u32 v18, v18, s11
	v_lshl_add_u64 v[90:91], v[18:19], 2, v[2:3]
	v_add_u32_e32 v18, 0x1a00, v1
	v_ashrrev_i32_e32 v63, 7, v18
	v_add_u32_e32 v18, s8, v63
	v_mul_lo_u32 v18, v18, s11
	v_lshl_add_u64 v[92:93], v[18:19], 2, v[2:3]
	v_add_u32_e32 v18, 0x1c00, v1
	v_ashrrev_i32_e32 v62, 7, v18
	v_add_u32_e32 v18, s8, v62
	v_mul_lo_u32 v18, v18, s11
	v_lshl_add_u64 v[94:95], v[18:19], 2, v[2:3]
	v_add_u32_e32 v18, 0x1e00, v1
	v_ashrrev_i32_e32 v61, 7, v18
	v_add_u32_e32 v18, s8, v61
	v_mul_lo_u32 v18, v18, s11
	v_lshl_add_u64 v[96:97], v[18:19], 2, v[2:3]
	v_lshlrev_b32_e32 v3, 1, v1
	v_and_b32_e32 v3, 62, v3
	s_movk_i32 s8, 0x204
	v_lshlrev_b32_e32 v18, 1, v3
	v_lshl_add_u32 v2, v17, 2, 0
	v_mad_u32_u24 v60, v3, s8, 0
	v_lshl_add_u64 v[20:21], s[6:7], 0, v[18:19]
	v_ashrrev_i32_e32 v22, 5, v1
	v_mul_lo_u32 v1, v16, s8
	v_mul_lo_u32 v3, v75, s8
	v_mul_lo_u32 v18, v74, s8
	v_mul_lo_u32 v45, v73, s8
	v_mul_lo_u32 v46, v72, s8
	v_mul_lo_u32 v47, v71, s8
	v_mul_lo_u32 v48, v70, s8
	v_mul_lo_u32 v49, v69, s8
	v_mul_lo_u32 v50, v68, s8
	v_mul_lo_u32 v51, v67, s8
	v_mul_lo_u32 v52, v66, s8
	v_mul_lo_u32 v53, v65, s8
	v_mul_lo_u32 v54, v64, s8
	v_mul_lo_u32 v55, v63, s8
	v_mul_lo_u32 v56, v62, s8
	v_mul_lo_u32 v57, v61, s8
	v_add_u32_e32 v42, v2, v1
	v_add_u32_e32 v43, v2, v3
	v_add_u32_e32 v44, v2, v18
	v_add_u32_e32 v45, v2, v45
	v_add_u32_e32 v46, v2, v46
	v_add_u32_e32 v47, v2, v47
	v_add_u32_e32 v48, v2, v48
	v_add_u32_e32 v49, v2, v49
	v_add_u32_e32 v50, v2, v50
	v_add_u32_e32 v51, v2, v51
	v_add_u32_e32 v52, v2, v52
	v_add_u32_e32 v53, v2, v53
	v_add_u32_e32 v54, v2, v54
	v_add_u32_e32 v55, v2, v55
	v_add_u32_e32 v56, v2, v56
	v_add_u32_e32 v57, v2, v57
	v_mul_lo_u32 v76, v16, s11
	global_load_dword v2, v[4:5], off
	global_load_dword v1, v[6:7], off
	s_nop 0
	global_load_dword v4, v[8:9], off
	global_load_dword v3, v[10:11], off
	global_load_dword v6, v[12:13], off
	global_load_dword v5, v[14:15], off
	s_nop 0
	global_load_dword v8, v[78:79], off
	global_load_dword v7, v[80:81], off
	global_load_dword v10, v[82:83], off
	global_load_dword v9, v[84:85], off
	global_load_dword v12, v[86:87], off
	global_load_dword v11, v[88:89], off
	global_load_dword v14, v[90:91], off
	global_load_dword v13, v[92:93], off
	global_load_dword v16, v[94:95], off
	global_load_dword v15, v[96:97], off
	v_ashrrev_i32_e32 v25, 5, v25
	v_ashrrev_i32_e32 v28, 5, v28
	v_ashrrev_i32_e32 v31, 5, v31
	v_ashrrev_i32_e32 v34, 5, v34
	v_ashrrev_i32_e32 v37, 5, v37
	v_ashrrev_i32_e32 v40, 5, v40
	v_ashrrev_i32_e32 v59, 5, v59
	s_add_i32 s8, s3, s12
	v_and_b32_e32 v23, 0x7f, v22
	v_lshl_add_u32 v24, v22, 2, v60
	v_and_b32_e32 v26, 0x7f, v25
	v_lshl_add_u32 v27, v25, 2, v60
	v_and_b32_e32 v29, 0x7f, v28
	v_lshl_add_u32 v30, v28, 2, v60
	v_and_b32_e32 v32, 0x7f, v31
	v_lshl_add_u32 v33, v31, 2, v60
	v_and_b32_e32 v35, 0x7f, v34
	v_lshl_add_u32 v36, v34, 2, v60
	v_and_b32_e32 v38, 0x7f, v37
	v_lshl_add_u32 v39, v37, 2, v60
	v_and_b32_e32 v41, 0x7f, v40
	v_lshl_add_u32 v58, v40, 2, v60
	v_lshl_add_u32 v60, v59, 2, v60
	s_lshl_b32 s13, s12, 6
	s_lshl_b32 s14, s3, 6
	v_mul_lo_u32 v61, v61, s11
	s_mul_i32 s15, s8, 0x2c000
	v_mul_lo_u32 v62, v62, s11
	v_mul_lo_u32 v63, v63, s11
	v_mul_lo_u32 v64, v64, s11
	v_mul_lo_u32 v65, v65, s11
	v_mul_lo_u32 v66, v66, s11
	v_mul_lo_u32 v67, v67, s11
	v_mul_lo_u32 v68, v68, s11
	v_mul_lo_u32 v69, v69, s11
	v_mul_lo_u32 v70, v70, s11
	v_mul_lo_u32 v71, v71, s11
	v_mul_lo_u32 v72, v72, s11
	v_mul_lo_u32 v73, v73, s11
	v_mul_lo_u32 v74, v74, s11
	v_mul_lo_u32 v75, v75, s11
	s_mov_b32 s16, 0x3fff00
	v_and_b32_e32 v77, 0x7f, v59
	s_waitcnt vmcnt(0)
	s_branch .LBB0_14

; #define LDS_BARRIER() do { asm volatile("s_waitcnt lgkmcnt(0)" ::: "memory"); __builtin_amdgcn_s_barrier(); asm volatile("" ::: "memory"); } while (0)
;     ...
;     const int cstride = nwg ? nwg : (int)gridDim.x; bid -= wg0;
;     if (bid < 0) return;
;     if (bid < ntiles) CONVW_LOAD(bid);
;     for (int t = bid; t < ntiles; t += cstride) {
;         const int n0 = (t / nkt) * 128, k0 = (t % nkt) * 64;
; #pragma unroll
;         for (int it = 0; it < 16; ++it) { const int e = tid + 512 * it, kk = e >> 7, nn = e & 127; tile[kk * 129 + nn] = v[it]; }
;         LDS_BARRIER();
;         if (t + cstride < ntiles) CONVW_LOAD(t + cstride);
.LBB0_14:
	s_waitcnt vmcnt(8)
	ds_write_b32 v42, v2
	ds_write_b32 v43, v1
	ds_write_b32 v44, v4
	ds_write_b32 v45, v3
	ds_write_b32 v46, v6
	ds_write_b32 v47, v5
	ds_write_b32 v48, v8
	ds_write_b32 v49, v7
	ds_write_b32 v50, v10
	ds_write_b32 v51, v9
	ds_write_b32 v52, v12
	ds_write_b32 v53, v11
	ds_write_b32 v54, v14
	ds_write_b32 v55, v13
	ds_write_b32 v56, v16
	ds_write_b32 v57, v15
	s_add_i32 s17, s12, s3
	s_waitcnt lgkmcnt(0)
	s_barrier
	s_cmpk_gt_i32 s17, 0x15f
	s_cselect_b64 s[8:9], -1, 0
	s_and_b64 vcc, exec, s[8:9]
	s_cbranch_vccnz .LBB0_13
	s_ashr_i32 s18, s17, 31
	s_lshr_b32 s18, s18, 28
	s_add_i32 s18, s17, s18
	s_ashr_i32 s18, s18, 4
	v_lshl_or_b32 v1, s18, 7, v17
	v_min_i32_e32 v2, 0xaff, v1
	s_mul_i32 s18, s18, 0xffd40000
	v_ashrrev_i32_e32 v3, 31, v2
	s_add_i32 s18, s18, s15
	v_lshl_add_u64 v[2:3], v[2:3], 2, s[70:71]
	v_add_u32_e32 v18, s18, v76
	v_lshl_add_u64 v[4:5], v[18:19], 2, v[2:3]
	v_add_u32_e32 v18, s18, v75
	v_lshl_add_u64 v[6:7], v[18:19], 2, v[2:3]
	v_add_u32_e32 v18, s18, v74
	v_lshl_add_u64 v[8:9], v[18:19], 2, v[2:3]
	v_add_u32_e32 v18, s18, v73
	v_lshl_add_u64 v[10:11], v[18:19], 2, v[2:3]
	v_add_u32_e32 v18, s18, v72
	v_lshl_add_u64 v[12:13], v[18:19], 2, v[2:3]
	v_add_u32_e32 v18, s18, v71
	v_lshl_add_u64 v[14:15], v[18:19], 2, v[2:3]
	v_add_u32_e32 v18, s18, v70
	v_lshl_add_u64 v[78:79], v[18:19], 2, v[2:3]
	v_add_u32_e32 v18, s18, v69
	v_lshl_add_u64 v[80:81], v[18:19], 2, v[2:3]
	v_add_u32_e32 v18, s18, v68
	global_load_dword v16, v[4:5], off
	global_load_dword v82, v[6:7], off
	global_load_dword v83, v[8:9], off
	global_load_dword v84, v[10:11], off
	global_load_dword v85, v[12:13], off
	global_load_dword v86, v[14:15], off
	global_load_dword v87, v[78:79], off
	s_nop 0
	global_load_dword v80, v[80:81], off
	v_lshl_add_u64 v[4:5], v[18:19], 2, v[2:3]
	v_add_u32_e32 v18, s18, v67
	v_lshl_add_u64 v[6:7], v[18:19], 2, v[2:3]
	v_add_u32_e32 v18, s18, v66
	v_lshl_add_u64 v[8:9], v[18:19], 2, v[2:3]
	v_add_u32_e32 v18, s18, v65
	v_lshl_add_u64 v[10:11], v[18:19], 2, v[2:3]
	v_add_u32_e32 v18, s18, v64
	v_lshl_add_u64 v[12:13], v[18:19], 2, v[2:3]
	v_add_u32_e32 v18, s18, v63
	v_lshl_add_u64 v[14:15], v[18:19], 2, v[2:3]
	v_add_u32_e32 v18, s18, v62
	v_lshl_add_u64 v[78:79], v[18:19], 2, v[2:3]
	v_add_u32_e32 v18, s18, v61
	v_lshl_add_u64 v[2:3], v[18:19], 2, v[2:3]
	global_load_dword v18, v[4:5], off
	global_load_dword v81, v[6:7], off
	global_load_dword v88, v[8:9], off
	s_nop 0
	global_load_dword v11, v[10:11], off
	s_nop 0
	global_load_dword v13, v[12:13], off
	s_nop 0
	global_load_dword v15, v[14:15], off
	s_nop 0
	global_load_dword v78, v[78:79], off
	s_nop 0
	global_load_dword v79, v[2:3], off
	v_cmp_gt_i32_e32 vcc, s11, v1
	s_waitcnt vmcnt(0)
	s_nop 0
	v_cndmask_b32_e32 v2, 0, v16, vcc
	v_cndmask_b32_e32 v1, 0, v82, vcc
	v_cndmask_b32_e32 v4, 0, v83, vcc
	v_cndmask_b32_e32 v3, 0, v84, vcc
	v_cndmask_b32_e32 v6, 0, v85, vcc
	v_cndmask_b32_e32 v5, 0, v86, vcc
	v_cndmask_b32_e32 v8, 0, v87, vcc
	v_cndmask_b32_e32 v7, 0, v80, vcc
	v_cndmask_b32_e32 v10, 0, v18, vcc
	v_cndmask_b32_e32 v9, 0, v81, vcc
	v_cndmask_b32_e32 v12, 0, v88, vcc
	v_cndmask_b32_e32 v11, 0, v11, vcc
	v_cndmask_b32_e32 v14, 0, v13, vcc
	v_cndmask_b32_e32 v13, 0, v15, vcc
	v_cndmask_b32_e32 v16, 0, v78, vcc
	v_cndmask_b32_e32 v15, 0, v79, vcc
	s_branch .LBB0_13
; #define LAUNDER_V(x) asm volatile("" : "+v"(x))
; #define LAUNDER_S(x) asm volatile("" : "+s"(x))
;     float* tile = (float*)ldsb;
;     int tid = threadIdx.x; LAUNDER_V(tid); int bid = blockIdx.x; LAUNDER_S(bid);
;     const int nkt = K / 64, ntiles = (Ntot / 128) * nkt;
;     float v[16];
;     ...
;     const int cstride = nwg ? nwg : (int)gridDim.x; bid -= wg0;
;     if (bid < 0) return;
;     if (bid < ntiles) CONVW_LOAD(bid);
.LBB0_16:
	v_mov_b32_e32 v1, v192
	s_mov_b32 s8, s52
	s_sub_i32 s9, s8, 32
	s_cmpk_gt_u32 s9, 0x15f
	s_cbranch_scc1 .LBB0_21
	s_lshl_b32 s11, s9, 3
	s_and_b32 s11, s11, 0xf80
	s_lshl_b32 s8, s8, 6
	v_and_b32_e32 v17, 0x7f, v1
	s_and_b32 s12, s8, 0x3c0
	v_or_b32_e32 v2, s11, v17
	v_ashrrev_i32_e32 v16, 7, v1
	v_add_u32_e32 v20, 0x200, v1
	v_lshlrev_b32_e32 v18, 2, v2
	v_mov_b32_e32 v19, 0
	v_add_u32_e32 v4, s12, v16
	s_movk_i32 s8, 0xb00
	v_ashrrev_i32_e32 v21, 7, v20
	v_add_u32_e32 v28, 0x400, v1
	s_waitcnt lgkmcnt(0)
	v_lshl_add_u64 v[2:3], s[80:81], 0, v[18:19]
	v_mul_lo_u32 v18, v4, s8
	v_add_u32_e32 v6, s12, v21
	v_ashrrev_i32_e32 v59, 7, v28
	v_add_u32_e32 v31, 0x600, v1
	v_lshl_add_u64 v[4:5], v[18:19], 2, v[2:3]
	v_mul_lo_u32 v18, v6, s8
	v_add_u32_e32 v8, s12, v59
	v_ashrrev_i32_e32 v58, 7, v31
	v_add_u32_e32 v34, 0x800, v1
	v_lshl_add_u64 v[6:7], v[18:19], 2, v[2:3]
	v_mul_lo_u32 v18, v8, s8
	v_add_u32_e32 v10, s12, v58
	v_ashrrev_i32_e32 v57, 7, v34
	v_add_u32_e32 v37, 0xa00, v1
	v_lshl_add_u64 v[8:9], v[18:19], 2, v[2:3]
	v_mul_lo_u32 v18, v10, s8
	v_add_u32_e32 v12, s12, v57
	v_ashrrev_i32_e32 v56, 7, v37
	v_lshl_add_u64 v[10:11], v[18:19], 2, v[2:3]
	v_mul_lo_u32 v18, v12, s8
	v_add_u32_e32 v14, s12, v56
	v_add_u32_e32 v40, 0xc00, v1
	v_lshl_add_u64 v[12:13], v[18:19], 2, v[2:3]
	v_mul_lo_u32 v18, v14, s8
	v_ashrrev_i32_e32 v55, 7, v40
	v_lshl_add_u64 v[14:15], v[18:19], 2, v[2:3]
	v_add_u32_e32 v18, s12, v55
	v_add_u32_e32 v43, 0xe00, v1
	v_mul_lo_u32 v18, v18, s8
	v_ashrrev_i32_e32 v54, 7, v43
	v_lshl_add_u64 v[80:81], v[18:19], 2, v[2:3]
	v_add_u32_e32 v18, s12, v54
	v_mul_lo_u32 v18, v18, s8
	v_lshl_add_u64 v[82:83], v[18:19], 2, v[2:3]
	v_add_u32_e32 v18, 0x1000, v1
	v_ashrrev_i32_e32 v53, 7, v18
	v_add_u32_e32 v18, s12, v53
	v_mul_lo_u32 v18, v18, s8
	v_lshl_add_u64 v[84:85], v[18:19], 2, v[2:3]
	v_add_u32_e32 v18, 0x1200, v1
	v_ashrrev_i32_e32 v52, 7, v18
	v_add_u32_e32 v18, s12, v52
	v_mul_lo_u32 v18, v18, s8
	v_lshl_add_u64 v[86:87], v[18:19], 2, v[2:3]
	v_add_u32_e32 v18, 0x1400, v1
	v_ashrrev_i32_e32 v51, 7, v18
	v_add_u32_e32 v18, s12, v51
	v_mul_lo_u32 v18, v18, s8
	v_lshl_add_u64 v[88:89], v[18:19], 2, v[2:3]
	v_add_u32_e32 v18, 0x1600, v1
	v_ashrrev_i32_e32 v50, 7, v18
	v_add_u32_e32 v18, s12, v50
	v_mul_lo_u32 v18, v18, s8
	v_lshl_add_u64 v[90:91], v[18:19], 2, v[2:3]
	v_add_u32_e32 v18, 0x1800, v1
	v_ashrrev_i32_e32 v49, 7, v18
	v_add_u32_e32 v18, s12, v49
	v_mul_lo_u32 v18, v18, s8
	v_lshl_add_u64 v[92:93], v[18:19], 2, v[2:3]
	v_add_u32_e32 v18, 0x1a00, v1
	v_ashrrev_i32_e32 v48, 7, v18
	v_add_u32_e32 v18, s12, v48
	v_mul_lo_u32 v18, v18, s8
	v_lshl_add_u64 v[94:95], v[18:19], 2, v[2:3]
	v_add_u32_e32 v18, 0x1c00, v1
	v_ashrrev_i32_e32 v47, 7, v18
	v_add_u32_e32 v18, s12, v47
	v_mul_lo_u32 v18, v18, s8
	v_lshl_add_u64 v[96:97], v[18:19], 2, v[2:3]
	v_add_u32_e32 v18, 0x1e00, v1
	v_ashrrev_i32_e32 v46, 7, v18
	v_add_u32_e32 v18, s12, v46
	v_mul_lo_u32 v18, v18, s8
	v_lshl_add_u64 v[98:99], v[18:19], 2, v[2:3]
	v_lshlrev_b32_e32 v3, 1, v1
	v_and_b32_e32 v3, 62, v3
	s_movk_i32 s11, 0x204
	v_lshl_add_u32 v2, v17, 2, 0
	v_mad_u32_u24 v45, v3, s11, 0
	v_lshlrev_b32_e32 v18, 1, v3
	v_ashrrev_i32_e32 v22, 5, v1
	v_mul_lo_u32 v1, v16, s11
	v_mul_lo_u32 v3, v21, s11
	v_mul_lo_u32 v64, v59, s11
	v_mul_lo_u32 v65, v58, s11
	v_mul_lo_u32 v66, v57, s11
	v_mul_lo_u32 v67, v56, s11
	v_mul_lo_u32 v68, v55, s11
	v_mul_lo_u32 v69, v54, s11
	v_mul_lo_u32 v70, v53, s11
	v_mul_lo_u32 v71, v52, s11
	v_mul_lo_u32 v72, v51, s11
	v_mul_lo_u32 v73, v50, s11
	v_mul_lo_u32 v74, v49, s11
	v_mul_lo_u32 v75, v48, s11
	v_mul_lo_u32 v76, v47, s11
	v_mul_lo_u32 v77, v46, s11
	v_mul_lo_u32 v61, v16, s8
	v_add_u32_e32 v62, v2, v1
	v_add_u32_e32 v63, v2, v3
	v_add_u32_e32 v64, v2, v64
	v_add_u32_e32 v65, v2, v65
	v_add_u32_e32 v66, v2, v66
	v_add_u32_e32 v67, v2, v67
	v_add_u32_e32 v68, v2, v68
	v_add_u32_e32 v69, v2, v69
	v_add_u32_e32 v70, v2, v70
	v_add_u32_e32 v71, v2, v71
	v_add_u32_e32 v72, v2, v72
	v_add_u32_e32 v73, v2, v73
	v_add_u32_e32 v74, v2, v74
	v_add_u32_e32 v75, v2, v75
	v_add_u32_e32 v76, v2, v76
	v_add_u32_e32 v77, v2, v77
	global_load_dword v2, v[4:5], off
	global_load_dword v1, v[6:7], off
	s_nop 0
	global_load_dword v4, v[8:9], off
	global_load_dword v3, v[10:11], off
	global_load_dword v6, v[12:13], off
	global_load_dword v5, v[14:15], off
	s_nop 0
	global_load_dword v8, v[80:81], off
	global_load_dword v7, v[82:83], off
	global_load_dword v10, v[84:85], off
	global_load_dword v9, v[86:87], off
	global_load_dword v12, v[88:89], off
	global_load_dword v11, v[90:91], off
	global_load_dword v14, v[92:93], off
	global_load_dword v13, v[94:95], off
	global_load_dword v16, v[96:97], off
	global_load_dword v15, v[98:99], off
	v_ashrrev_i32_e32 v25, 5, v20
	v_ashrrev_i32_e32 v28, 5, v28
	v_ashrrev_i32_e32 v31, 5, v31
	v_ashrrev_i32_e32 v34, 5, v34
	v_ashrrev_i32_e32 v37, 5, v37
	v_ashrrev_i32_e32 v40, 5, v40
	v_ashrrev_i32_e32 v43, 5, v43
	s_add_i32 s13, s3, s9
	v_and_b32_e32 v23, 0x7f, v22
	v_lshl_add_u32 v24, v22, 2, v45
	v_and_b32_e32 v26, 0x7f, v25
	v_lshl_add_u32 v27, v25, 2, v45
	v_and_b32_e32 v29, 0x7f, v28
	v_lshl_add_u32 v30, v28, 2, v45
	v_and_b32_e32 v32, 0x7f, v31
	v_lshl_add_u32 v33, v31, 2, v45
	v_and_b32_e32 v35, 0x7f, v34
	v_lshl_add_u32 v36, v34, 2, v45
	v_and_b32_e32 v38, 0x7f, v37
	v_lshl_add_u32 v39, v37, 2, v45
	v_and_b32_e32 v41, 0x7f, v40
	v_lshl_add_u32 v42, v40, 2, v45
	v_and_b32_e32 v44, 0x7f, v43
	v_lshl_add_u32 v45, v43, 2, v45
	s_lshl_b32 s11, s9, 6
	s_lshl_b32 s12, s3, 6
	v_mul_lo_u32 v46, v46, s8
	s_mul_i32 s13, s13, 0x2c000
	v_mul_lo_u32 v47, v47, s8
	v_mul_lo_u32 v48, v48, s8
	v_mul_lo_u32 v49, v49, s8
	v_mul_lo_u32 v50, v50, s8
	v_mul_lo_u32 v51, v51, s8
	v_mul_lo_u32 v52, v52, s8
	v_mul_lo_u32 v53, v53, s8
	v_mul_lo_u32 v54, v54, s8
	v_mul_lo_u32 v55, v55, s8
	v_mul_lo_u32 v56, v56, s8
	v_mul_lo_u32 v57, v57, s8
	v_mul_lo_u32 v58, v58, s8
	v_mul_lo_u32 v59, v59, s8
	v_mul_lo_u32 v60, v21, s8
	s_mov_b32 s14, 0x3fff00
	v_mov_b32_e32 v78, 0x20000
	v_lshl_add_u64 v[20:21], s[6:7], 0, v[18:19]
	s_waitcnt vmcnt(0)
	s_branch .LBB0_19

; #define LDS_BARRIER() do { asm volatile("s_waitcnt lgkmcnt(0)" ::: "memory"); __builtin_amdgcn_s_barrier(); asm volatile("" ::: "memory"); } while (0)
;     ...
;     const int cstride = nwg ? nwg : (int)gridDim.x; bid -= wg0;
;     if (bid < 0) return;
;     if (bid < ntiles) CONVW_LOAD(bid);
;     for (int t = bid; t < ntiles; t += cstride) {
;         const int n0 = (t / nkt) * 128, k0 = (t % nkt) * 64;
; #pragma unroll
;         for (int it = 0; it < 16; ++it) { const int e = tid + 512 * it, kk = e >> 7, nn = e & 127; tile[kk * 129 + nn] = v[it]; }
;         LDS_BARRIER();
;         if (t + cstride < ntiles) CONVW_LOAD(t + cstride);
.LBB0_19:
	s_waitcnt vmcnt(8)
	ds_write_b32 v62, v2
	ds_write_b32 v63, v1
	ds_write_b32 v64, v4
	ds_write_b32 v65, v3
	ds_write_b32 v66, v6
	ds_write_b32 v67, v5
	ds_write_b32 v68, v8
	ds_write_b32 v69, v7
	ds_write_b32 v70, v10
	ds_write_b32 v71, v9
	ds_write_b32 v72, v12
	ds_write_b32 v73, v11
	ds_write_b32 v74, v14
	ds_write_b32 v75, v13
	ds_write_b32 v76, v16
	ds_write_b32 v77, v15
	s_add_i32 s15, s9, s3
	s_waitcnt lgkmcnt(0)
	s_barrier
	s_cmpk_gt_i32 s15, 0x15f
	s_cselect_b64 s[6:7], -1, 0
	s_and_b64 vcc, exec, s[6:7]
	s_cbranch_vccnz .LBB0_18
	s_ashr_i32 s16, s15, 31
	s_lshr_b32 s16, s16, 28
	s_add_i32 s16, s15, s16
	s_ashr_i32 s16, s16, 4
	v_lshl_or_b32 v1, s16, 7, v17
	v_min_i32_e32 v2, 0xaff, v1
	s_mul_i32 s16, s16, 0xffd40000
	v_ashrrev_i32_e32 v3, 31, v2
	s_add_i32 s16, s16, s13
	v_lshl_add_u64 v[2:3], v[2:3], 2, s[80:81]
	v_add_u32_e32 v18, s16, v61
	v_lshl_add_u64 v[4:5], v[18:19], 2, v[2:3]
	v_add_u32_e32 v18, s16, v60
	v_lshl_add_u64 v[6:7], v[18:19], 2, v[2:3]
	v_add_u32_e32 v18, s16, v59
	v_lshl_add_u64 v[8:9], v[18:19], 2, v[2:3]
	v_add_u32_e32 v18, s16, v58
	v_lshl_add_u64 v[10:11], v[18:19], 2, v[2:3]
	v_add_u32_e32 v18, s16, v57
	v_lshl_add_u64 v[12:13], v[18:19], 2, v[2:3]
	v_add_u32_e32 v18, s16, v56
	v_lshl_add_u64 v[14:15], v[18:19], 2, v[2:3]
	v_add_u32_e32 v18, s16, v55
	v_lshl_add_u64 v[80:81], v[18:19], 2, v[2:3]
	v_add_u32_e32 v18, s16, v54
	v_lshl_add_u64 v[82:83], v[18:19], 2, v[2:3]
	v_add_u32_e32 v18, s16, v53
	global_load_dword v16, v[4:5], off
	global_load_dword v79, v[6:7], off
	global_load_dword v84, v[8:9], off
	global_load_dword v85, v[10:11], off
	global_load_dword v86, v[12:13], off
	global_load_dword v87, v[14:15], off
	global_load_dword v88, v[80:81], off
	s_nop 0
	global_load_dword v82, v[82:83], off
	v_lshl_add_u64 v[4:5], v[18:19], 2, v[2:3]
	v_add_u32_e32 v18, s16, v52
	v_lshl_add_u64 v[6:7], v[18:19], 2, v[2:3]
	v_add_u32_e32 v18, s16, v51
	v_lshl_add_u64 v[8:9], v[18:19], 2, v[2:3]
	v_add_u32_e32 v18, s16, v50
	v_lshl_add_u64 v[10:11], v[18:19], 2, v[2:3]
	v_add_u32_e32 v18, s16, v49
	v_lshl_add_u64 v[12:13], v[18:19], 2, v[2:3]
	v_add_u32_e32 v18, s16, v48
	v_lshl_add_u64 v[14:15], v[18:19], 2, v[2:3]
	v_add_u32_e32 v18, s16, v47
	v_lshl_add_u64 v[80:81], v[18:19], 2, v[2:3]
	v_add_u32_e32 v18, s16, v46
	v_lshl_add_u64 v[2:3], v[18:19], 2, v[2:3]
	global_load_dword v18, v[4:5], off
	global_load_dword v83, v[6:7], off
	global_load_dword v89, v[8:9], off
	s_nop 0
	global_load_dword v11, v[10:11], off
	s_nop 0
	global_load_dword v13, v[12:13], off
	s_nop 0
	global_load_dword v15, v[14:15], off
	s_nop 0
	global_load_dword v80, v[80:81], off
	s_nop 0
	global_load_dword v81, v[2:3], off
	v_cmp_gt_i32_e32 vcc, s8, v1
	s_waitcnt vmcnt(15)
	s_nop 0
	v_cndmask_b32_e32 v2, 0, v16, vcc
	s_waitcnt vmcnt(14)
	v_cndmask_b32_e32 v1, 0, v79, vcc
	s_waitcnt vmcnt(13)
	v_cndmask_b32_e32 v4, 0, v84, vcc
	s_waitcnt vmcnt(12)
	v_cndmask_b32_e32 v3, 0, v85, vcc
	s_waitcnt vmcnt(11)
	v_cndmask_b32_e32 v6, 0, v86, vcc
	s_waitcnt vmcnt(10)
	v_cndmask_b32_e32 v5, 0, v87, vcc
	s_waitcnt vmcnt(9)
	v_cndmask_b32_e32 v8, 0, v88, vcc
	s_waitcnt vmcnt(8)
	v_cndmask_b32_e32 v7, 0, v82, vcc
	s_waitcnt vmcnt(7)
	v_cndmask_b32_e32 v10, 0, v18, vcc
	s_waitcnt vmcnt(6)
	v_cndmask_b32_e32 v9, 0, v83, vcc
	s_waitcnt vmcnt(5)
	v_cndmask_b32_e32 v12, 0, v89, vcc
	s_waitcnt vmcnt(4)
	v_cndmask_b32_e32 v11, 0, v11, vcc
	s_waitcnt vmcnt(3)
	v_cndmask_b32_e32 v14, 0, v13, vcc
	s_waitcnt vmcnt(2)
	v_cndmask_b32_e32 v13, 0, v15, vcc
	s_waitcnt vmcnt(1)
	v_cndmask_b32_e32 v16, 0, v80, vcc
	s_waitcnt vmcnt(0)
	v_cndmask_b32_e32 v15, 0, v81, vcc
	s_branch .LBB0_18
; #define LAUNDER_V(x) asm volatile("" : "+v"(x))
; #define LAUNDER_S(x) asm volatile("" : "+s"(x))
;     float* tile = (float*)ldsb;
;     int tid = threadIdx.x; LAUNDER_V(tid); int bid = blockIdx.x; LAUNDER_S(bid);
;     const int nkt = K / 64, ntiles = (Ntot / 128) * nkt;
;     float v[16];
;     ...
;     const int cstride = nwg ? nwg : (int)gridDim.x; bid -= wg0;
;     if (bid < 0) return;
;     if (bid < ntiles) CONVW_LOAD(bid);
.LBB0_21:
	v_mov_b32_e32 v1, v192
	s_mov_b32 s6, s52
	s_sub_i32 s7, s6, 32
	s_cmpk_gt_u32 s7, 0x15f
	s_cbranch_scc1 .LBB0_26
	s_and_b32 s6, s7, 0xffff
	s_mul_i32 s6, s6, 0xba2f
	s_lshr_b32 s8, s6, 21
	s_lshr_b32 s6, s6, 14
	s_mul_i32 s8, s8, 44
	s_and_b32 s6, s6, 0xff80
	s_sub_i32 s8, s7, s8
	v_and_b32_e32 v17, 0x7f, v1
	s_lshl_b32 s8, s8, 6
	v_or_b32_e32 v2, s6, v17
	s_and_b32 s8, s8, 0xffc0
	v_lshlrev_b32_e32 v18, 2, v2
	v_mov_b32_e32 v19, 0
	v_ashrrev_i32_e32 v16, 7, v1
	v_add_u32_e32 v24, 0x200, v1
	s_waitcnt lgkmcnt(0)
	v_lshl_add_u64 v[2:3], s[82:83], 0, v[18:19]
	v_add_lshl_u32 v18, v16, s8, 10
	v_ashrrev_i32_e32 v52, 7, v24
	v_add_u32_e32 v26, 0x400, v1
	v_lshl_add_u64 v[4:5], v[18:19], 2, v[2:3]
	v_add_lshl_u32 v18, v52, s8, 10
	v_ashrrev_i32_e32 v51, 7, v26
	v_add_u32_e32 v28, 0x600, v1
	v_lshl_add_u64 v[6:7], v[18:19], 2, v[2:3]
	v_add_lshl_u32 v18, v51, s8, 10
	v_ashrrev_i32_e32 v50, 7, v28
	v_add_u32_e32 v30, 0x800, v1
	v_lshl_add_u64 v[8:9], v[18:19], 2, v[2:3]
	v_add_lshl_u32 v18, v50, s8, 10
	v_ashrrev_i32_e32 v49, 7, v30
	v_add_u32_e32 v32, 0xa00, v1
	v_lshl_add_u64 v[10:11], v[18:19], 2, v[2:3]
	v_add_lshl_u32 v18, v49, s8, 10
	v_ashrrev_i32_e32 v48, 7, v32
	v_add_u32_e32 v34, 0xc00, v1
	v_lshl_add_u64 v[12:13], v[18:19], 2, v[2:3]
	v_add_lshl_u32 v18, v48, s8, 10
	v_ashrrev_i32_e32 v47, 7, v34
	v_add_u32_e32 v36, 0xe00, v1
	v_lshl_add_u64 v[14:15], v[18:19], 2, v[2:3]
	v_add_lshl_u32 v18, v47, s8, 10
	v_ashrrev_i32_e32 v46, 7, v36
	v_lshl_add_u64 v[70:71], v[18:19], 2, v[2:3]
	v_add_lshl_u32 v18, v46, s8, 10
	v_lshl_add_u64 v[72:73], v[18:19], 2, v[2:3]
	v_add_u32_e32 v18, 0x1000, v1
	v_ashrrev_i32_e32 v45, 7, v18
	v_add_lshl_u32 v18, v45, s8, 10
	v_lshl_add_u64 v[74:75], v[18:19], 2, v[2:3]
	v_add_u32_e32 v18, 0x1200, v1
	v_ashrrev_i32_e32 v44, 7, v18
	v_add_lshl_u32 v18, v44, s8, 10
	v_lshl_add_u64 v[76:77], v[18:19], 2, v[2:3]
	v_add_u32_e32 v18, 0x1400, v1
	v_ashrrev_i32_e32 v43, 7, v18
	v_add_lshl_u32 v18, v43, s8, 10
	v_lshl_add_u64 v[78:79], v[18:19], 2, v[2:3]
	v_add_u32_e32 v18, 0x1600, v1
	v_ashrrev_i32_e32 v42, 7, v18
	v_add_lshl_u32 v18, v42, s8, 10
	v_lshl_add_u64 v[80:81], v[18:19], 2, v[2:3]
	v_add_u32_e32 v18, 0x1800, v1
	v_ashrrev_i32_e32 v41, 7, v18
	v_add_lshl_u32 v18, v41, s8, 10
	v_lshl_add_u64 v[82:83], v[18:19], 2, v[2:3]
	v_add_u32_e32 v18, 0x1a00, v1
	v_ashrrev_i32_e32 v40, 7, v18
	v_add_lshl_u32 v18, v40, s8, 10
	v_lshl_add_u64 v[84:85], v[18:19], 2, v[2:3]
	v_add_u32_e32 v18, 0x1c00, v1
	v_ashrrev_i32_e32 v39, 7, v18
	v_add_lshl_u32 v18, v39, s8, 10
	v_lshl_add_u64 v[86:87], v[18:19], 2, v[2:3]
	v_add_u32_e32 v18, 0x1e00, v1
	v_ashrrev_i32_e32 v38, 7, v18
	v_add_lshl_u32 v18, v38, s8, 10
	v_lshl_add_u64 v[88:89], v[18:19], 2, v[2:3]
	v_lshlrev_b32_e32 v2, 1, v1
	v_and_b32_e32 v2, 62, v2
	s_movk_i32 s8, 0x204
	v_lshlrev_b32_e32 v18, 1, v2
	v_mad_u32_u24 v37, v2, s8, 0
	v_lshl_add_u64 v[2:3], s[0:1], 0, v[18:19]
	s_mov_b64 s[0:1], 0x17c00000
	v_lshl_add_u32 v69, v17, 2, 0
	v_lshl_add_u64 v[20:21], v[2:3], 0, s[0:1]
	v_ashrrev_i32_e32 v22, 5, v1
	v_mul_lo_u32 v1, v16, s8
	v_mul_lo_u32 v2, v52, s8
	v_mul_lo_u32 v3, v51, s8
	v_lshlrev_b32_e32 v53, 10, v16
	v_add_u32_e32 v54, v69, v1
	v_add_u32_e32 v55, v69, v2
	v_add_u32_e32 v56, v69, v3
	global_load_dword v2, v[4:5], off
	global_load_dword v1, v[6:7], off
	s_nop 0
	global_load_dword v4, v[8:9], off
	global_load_dword v3, v[10:11], off
	global_load_dword v6, v[12:13], off
	global_load_dword v5, v[14:15], off
	s_nop 0
	global_load_dword v8, v[70:71], off
	global_load_dword v7, v[72:73], off
	global_load_dword v10, v[74:75], off
	global_load_dword v9, v[76:77], off
	global_load_dword v12, v[78:79], off
	global_load_dword v11, v[80:81], off
	global_load_dword v14, v[82:83], off
	global_load_dword v13, v[84:85], off
	global_load_dword v16, v[86:87], off
	global_load_dword v15, v[88:89], off
	v_mul_lo_u32 v18, v50, s8
	v_mul_lo_u32 v58, v49, s8
	v_mul_lo_u32 v59, v48, s8
	v_mul_lo_u32 v60, v47, s8
	v_mul_lo_u32 v61, v46, s8
	v_mul_lo_u32 v62, v45, s8
	v_mul_lo_u32 v63, v44, s8
	v_mul_lo_u32 v64, v43, s8
	v_mul_lo_u32 v65, v42, s8
	v_mul_lo_u32 v66, v41, s8
	v_mul_lo_u32 v67, v40, s8
	v_mul_lo_u32 v68, v39, s8
	v_mul_lo_u32 v90, v38, s8
	v_ashrrev_i32_e32 v24, 5, v24
	v_ashrrev_i32_e32 v26, 5, v26
	v_ashrrev_i32_e32 v28, 5, v28
	v_ashrrev_i32_e32 v30, 5, v30
	v_ashrrev_i32_e32 v32, 5, v32
	v_ashrrev_i32_e32 v34, 5, v34
	v_ashrrev_i32_e32 v36, 5, v36
	s_add_i32 s0, s3, s7
	s_movk_i32 s6, 0x400
	v_lshl_add_u32 v23, v22, 2, v37
	v_lshl_add_u32 v25, v24, 2, v37
	v_lshl_add_u32 v27, v26, 2, v37
	v_lshl_add_u32 v29, v28, 2, v37
	v_lshl_add_u32 v31, v30, 2, v37
	v_lshl_add_u32 v33, v32, 2, v37
	v_lshl_add_u32 v35, v34, 2, v37
	v_lshl_add_u32 v37, v36, 2, v37
	s_lshl_b32 s8, s7, 6
	s_lshl_b32 s9, s3, 6
	v_lshlrev_b32_e32 v38, 10, v38
	s_lshl_b32 s10, s0, 16
	s_lshl_b32 s11, s3, 16
	v_lshlrev_b32_e32 v39, 10, v39
	v_lshlrev_b32_e32 v40, 10, v40
	v_lshlrev_b32_e32 v41, 10, v41
	v_lshlrev_b32_e32 v42, 10, v42
	v_lshlrev_b32_e32 v43, 10, v43
	v_lshlrev_b32_e32 v44, 10, v44
	v_lshlrev_b32_e32 v45, 10, v45
	v_lshlrev_b32_e32 v46, 10, v46
	v_lshlrev_b32_e32 v47, 10, v47
	v_lshlrev_b32_e32 v48, 10, v48
	v_lshlrev_b32_e32 v49, 10, v49
	v_lshlrev_b32_e32 v50, 10, v50
	v_lshlrev_b32_e32 v51, 10, v51
	v_lshlrev_b32_e32 v52, 10, v52
	v_add_u32_e32 v57, v69, v18
	v_add_u32_e32 v58, v69, v58
	v_add_u32_e32 v59, v69, v59
	v_add_u32_e32 v60, v69, v60
	v_add_u32_e32 v61, v69, v61
	v_add_u32_e32 v62, v69, v62
	v_add_u32_e32 v63, v69, v63
	v_add_u32_e32 v64, v69, v64
	v_add_u32_e32 v65, v69, v65
	v_add_u32_e32 v66, v69, v66
	v_add_u32_e32 v67, v69, v67
	v_add_u32_e32 v68, v69, v68
	v_add_u32_e32 v69, v69, v90
	s_movk_i32 s12, 0xb00
	s_waitcnt vmcnt(0)
	s_branch .LBB0_24

; #define LDS_BARRIER() do { asm volatile("s_waitcnt lgkmcnt(0)" ::: "memory"); __builtin_amdgcn_s_barrier(); asm volatile("" ::: "memory"); } while (0)
;     ...
;     const int cstride = nwg ? nwg : (int)gridDim.x; bid -= wg0;
;     if (bid < 0) return;
;     if (bid < ntiles) CONVW_LOAD(bid);
;     for (int t = bid; t < ntiles; t += cstride) {
;         const int n0 = (t / nkt) * 128, k0 = (t % nkt) * 64;
; #pragma unroll
;         for (int it = 0; it < 16; ++it) { const int e = tid + 512 * it, kk = e >> 7, nn = e & 127; tile[kk * 129 + nn] = v[it]; }
;         LDS_BARRIER();
;         if (t + cstride < ntiles) CONVW_LOAD(t + cstride);
.LBB0_24:
	s_waitcnt vmcnt(8)
	ds_write_b32 v54, v2
	ds_write_b32 v55, v1
	ds_write_b32 v56, v4
	ds_write_b32 v57, v3
	ds_write_b32 v58, v6
	ds_write_b32 v59, v5
	ds_write_b32 v60, v8
	ds_write_b32 v61, v7
	ds_write_b32 v62, v10
	ds_write_b32 v63, v9
	ds_write_b32 v64, v12
	ds_write_b32 v65, v11
	ds_write_b32 v66, v14
	ds_write_b32 v67, v13
	ds_write_b32 v68, v16
	ds_write_b32 v69, v15
	s_add_i32 s13, s7, s3
	s_waitcnt lgkmcnt(0)
	s_barrier
	s_cmpk_gt_i32 s13, 0x15f
	s_cselect_b64 s[0:1], -1, 0
	s_and_b64 vcc, exec, s[0:1]
	s_cbranch_vccnz .LBB0_23
	s_mul_hi_i32 s14, s13, 0x2e8ba2e9
	s_lshr_b32 s15, s14, 31
	s_ashr_i32 s14, s14, 3
	s_add_i32 s14, s14, s15
	v_lshl_or_b32 v1, s14, 7, v17
	v_min_i32_e32 v2, 0x3ff, v1
	s_mul_i32 s14, s14, 0xffd40000
	v_ashrrev_i32_e32 v3, 31, v2
	s_add_i32 s14, s14, s10
	v_lshl_add_u64 v[2:3], v[2:3], 2, s[82:83]
	v_add_u32_e32 v18, s14, v53
	v_lshl_add_u64 v[4:5], v[18:19], 2, v[2:3]
	v_add_u32_e32 v18, s14, v52
	v_lshl_add_u64 v[6:7], v[18:19], 2, v[2:3]
	v_add_u32_e32 v18, s14, v51
	v_lshl_add_u64 v[8:9], v[18:19], 2, v[2:3]
	v_add_u32_e32 v18, s14, v50
	v_lshl_add_u64 v[10:11], v[18:19], 2, v[2:3]
	v_add_u32_e32 v18, s14, v49
	v_lshl_add_u64 v[12:13], v[18:19], 2, v[2:3]
	v_add_u32_e32 v18, s14, v48
	v_lshl_add_u64 v[14:15], v[18:19], 2, v[2:3]
	v_add_u32_e32 v18, s14, v47
	v_lshl_add_u64 v[70:71], v[18:19], 2, v[2:3]
	v_add_u32_e32 v18, s14, v46
	v_lshl_add_u64 v[72:73], v[18:19], 2, v[2:3]
	v_add_u32_e32 v18, s14, v45
	global_load_dword v16, v[4:5], off
	global_load_dword v74, v[6:7], off
	global_load_dword v75, v[8:9], off
	global_load_dword v76, v[10:11], off
	global_load_dword v77, v[12:13], off
	global_load_dword v78, v[14:15], off
	global_load_dword v79, v[70:71], off
	s_nop 0
	global_load_dword v72, v[72:73], off
	v_lshl_add_u64 v[4:5], v[18:19], 2, v[2:3]
	v_add_u32_e32 v18, s14, v44
	v_lshl_add_u64 v[6:7], v[18:19], 2, v[2:3]
	v_add_u32_e32 v18, s14, v43
	v_lshl_add_u64 v[8:9], v[18:19], 2, v[2:3]
	v_add_u32_e32 v18, s14, v42
	v_lshl_add_u64 v[10:11], v[18:19], 2, v[2:3]
	v_add_u32_e32 v18, s14, v41
	v_lshl_add_u64 v[12:13], v[18:19], 2, v[2:3]
	v_add_u32_e32 v18, s14, v40
	v_lshl_add_u64 v[14:15], v[18:19], 2, v[2:3]
	v_add_u32_e32 v18, s14, v39
	v_lshl_add_u64 v[70:71], v[18:19], 2, v[2:3]
	v_add_u32_e32 v18, s14, v38
	v_lshl_add_u64 v[2:3], v[18:19], 2, v[2:3]
	global_load_dword v18, v[4:5], off
	global_load_dword v73, v[6:7], off
	global_load_dword v80, v[8:9], off
	s_nop 0
	global_load_dword v11, v[10:11], off
	s_nop 0
	global_load_dword v13, v[12:13], off
	s_nop 0
	global_load_dword v15, v[14:15], off
	s_nop 0
	global_load_dword v70, v[70:71], off
	s_nop 0
	global_load_dword v71, v[2:3], off
	v_cmp_gt_i32_e32 vcc, s6, v1
	s_waitcnt vmcnt(15)
	s_nop 0
	v_cndmask_b32_e32 v2, 0, v16, vcc
	s_waitcnt vmcnt(14)
	v_cndmask_b32_e32 v1, 0, v74, vcc
	s_waitcnt vmcnt(13)
	v_cndmask_b32_e32 v4, 0, v75, vcc
	s_waitcnt vmcnt(12)
	v_cndmask_b32_e32 v3, 0, v76, vcc
	s_waitcnt vmcnt(11)
	v_cndmask_b32_e32 v6, 0, v77, vcc
	s_waitcnt vmcnt(10)
	v_cndmask_b32_e32 v5, 0, v78, vcc
	s_waitcnt vmcnt(9)
	v_cndmask_b32_e32 v8, 0, v79, vcc
	s_waitcnt vmcnt(8)
	v_cndmask_b32_e32 v7, 0, v72, vcc
	s_waitcnt vmcnt(7)
	v_cndmask_b32_e32 v10, 0, v18, vcc
	s_waitcnt vmcnt(6)
	v_cndmask_b32_e32 v9, 0, v73, vcc
	s_waitcnt vmcnt(5)
	v_cndmask_b32_e32 v12, 0, v80, vcc
	s_waitcnt vmcnt(4)
	v_cndmask_b32_e32 v11, 0, v11, vcc
	s_waitcnt vmcnt(3)
	v_cndmask_b32_e32 v14, 0, v13, vcc
	s_waitcnt vmcnt(2)
	v_cndmask_b32_e32 v13, 0, v15, vcc
	s_waitcnt vmcnt(1)
	v_cndmask_b32_e32 v16, 0, v70, vcc
	s_waitcnt vmcnt(0)
	v_cndmask_b32_e32 v15, 0, v71, vcc
	s_branch .LBB0_23

; #define LAUNDER_V(x) asm volatile("" : "+v"(x))
; #define LAUNDER_S(x) asm volatile("" : "+s"(x))
;     float* tile = (float*)ldsb;
;     int tid = threadIdx.x; LAUNDER_V(tid); int bid = blockIdx.x; LAUNDER_S(bid);
;     const int nkt = K / 64, ntiles = (Ntot / 128) * nkt;
;     float v[16];
;     ...
;     const int cstride = nwg ? nwg : (int)gridDim.x; bid -= wg0;
;     if (bid < 0) return;
;     if (bid < ntiles) CONVW_LOAD(bid);
.LBB0_227:
	v_readlane_b32 s0, v255, 16
	v_readlane_b32 s1, v255, 17
	s_and_b64 s[0:1], s[0:1], exec
	v_mov_b32_e32 v18, v192
	s_mov_b32 s4, s52
	s_cselect_b32 s3, 0x100000, 0
	s_and_b32 s0, s4, 0xffffff80
	s_cmpk_lg_i32 s0, 0x80
	s_cbranch_scc1 .LBB0_232
	v_readlane_b32 s8, v253, 34
	s_lshl_b32 s0, s3, 2
	v_readlane_b32 s22, v253, 48
	v_readlane_b32 s10, v253, 36
	v_readlane_b32 s23, v253, 49
	s_add_u32 s0, s22, s0
	s_addc_u32 s1, s23, 0
	s_add_i32 s10, s4, 0xffffff80
	s_lshl_b32 s5, s10, 3
	s_and_b32 s5, s5, 0x380
	v_and_b32_e32 v20, 0x7f, v18
	s_lshl_b32 s4, s4, 6
	v_or_b32_e32 v0, s5, v20
	s_and_b32 s4, s4, 0x3c0
	v_lshlrev_b32_e32 v32, 2, v0
	v_ashrrev_i32_e32 v19, 7, v18
	v_add_u32_e32 v23, 0x200, v18
	v_lshl_add_u64 v[16:17], s[0:1], 0, v[32:33]
	v_add_lshl_u32 v32, s4, v19, 10
	v_ashrrev_i32_e32 v53, 7, v23
	v_add_u32_e32 v25, 0x400, v18
	v_lshl_add_u64 v[0:1], v[32:33], 2, v[16:17]
	v_add_lshl_u32 v32, s4, v53, 10
	v_ashrrev_i32_e32 v52, 7, v25
	v_add_u32_e32 v27, 0x600, v18
	v_lshl_add_u64 v[2:3], v[32:33], 2, v[16:17]
	v_add_lshl_u32 v32, s4, v52, 10
	v_ashrrev_i32_e32 v51, 7, v27
	v_add_u32_e32 v29, 0x800, v18
	global_load_dword v0, v[0:1], off
	v_ashrrev_i32_e32 v50, 7, v29
	global_load_dword v1, v[2:3], off
	v_lshl_add_u64 v[2:3], v[32:33], 2, v[16:17]
	v_add_lshl_u32 v32, s4, v51, 10
	v_add_u32_e32 v31, 0xa00, v18
	v_lshl_add_u64 v[4:5], v[32:33], 2, v[16:17]
	v_add_lshl_u32 v32, s4, v50, 10
	v_ashrrev_i32_e32 v49, 7, v31
	v_add_u32_e32 v35, 0xc00, v18
	global_load_dword v2, v[2:3], off
	v_ashrrev_i32_e32 v48, 7, v35
	global_load_dword v3, v[4:5], off
	v_lshl_add_u64 v[4:5], v[32:33], 2, v[16:17]
	v_add_lshl_u32 v32, s4, v49, 10
	v_add_u32_e32 v37, 0xe00, v18
	v_lshl_add_u64 v[6:7], v[32:33], 2, v[16:17]
	v_add_lshl_u32 v32, s4, v48, 10
	v_ashrrev_i32_e32 v47, 7, v37
	global_load_dword v4, v[4:5], off
	v_readlane_b32 s9, v253, 35
	global_load_dword v5, v[6:7], off
	v_lshl_add_u64 v[6:7], v[32:33], 2, v[16:17]
	v_add_lshl_u32 v32, s4, v47, 10
	v_lshl_add_u64 v[8:9], v[32:33], 2, v[16:17]
	global_load_dword v6, v[6:7], off
	v_lshl_add_u32 v70, v20, 2, 0
	global_load_dword v7, v[8:9], off
	v_add_u32_e32 v8, 0x1000, v18
	v_ashrrev_i32_e32 v46, 7, v8
	v_add_lshl_u32 v32, s4, v46, 10
	v_lshl_add_u64 v[8:9], v[32:33], 2, v[16:17]
	global_load_dword v8, v[8:9], off
	v_add_u32_e32 v9, 0x1200, v18
	v_ashrrev_i32_e32 v45, 7, v9
	v_add_lshl_u32 v32, s4, v45, 10
	v_lshl_add_u64 v[10:11], v[32:33], 2, v[16:17]
	global_load_dword v9, v[10:11], off
	v_add_u32_e32 v10, 0x1400, v18
	v_ashrrev_i32_e32 v44, 7, v10
	v_add_lshl_u32 v32, s4, v44, 10
	v_lshl_add_u64 v[10:11], v[32:33], 2, v[16:17]
	global_load_dword v10, v[10:11], off
	v_add_u32_e32 v11, 0x1600, v18
	v_ashrrev_i32_e32 v43, 7, v11
	v_add_lshl_u32 v32, s4, v43, 10
	v_lshl_add_u64 v[12:13], v[32:33], 2, v[16:17]
	global_load_dword v11, v[12:13], off
	v_add_u32_e32 v12, 0x1800, v18
	v_ashrrev_i32_e32 v42, 7, v12
	v_add_lshl_u32 v32, s4, v42, 10
	v_lshl_add_u64 v[12:13], v[32:33], 2, v[16:17]
	global_load_dword v12, v[12:13], off
	v_add_u32_e32 v13, 0x1a00, v18
	v_ashrrev_i32_e32 v41, 7, v13
	v_add_lshl_u32 v32, s4, v41, 10
	v_lshl_add_u64 v[14:15], v[32:33], 2, v[16:17]
	global_load_dword v13, v[14:15], off
	v_add_u32_e32 v14, 0x1c00, v18
	v_ashrrev_i32_e32 v40, 7, v14
	v_add_lshl_u32 v32, s4, v40, 10
	v_lshl_add_u64 v[14:15], v[32:33], 2, v[16:17]
	global_load_dword v14, v[14:15], off
	v_add_u32_e32 v15, 0x1e00, v18
	v_ashrrev_i32_e32 v39, 7, v15
	v_add_lshl_u32 v32, s4, v39, 10
	v_lshl_add_u64 v[16:17], v[32:33], 2, v[16:17]
	global_load_dword v15, v[16:17], off
	v_lshlrev_b32_e32 v16, 1, v18
	v_and_b32_e32 v16, 62, v16
	v_readlane_b32 s4, v255, 7
	v_lshlrev_b32_e32 v32, 1, v16
	v_readlane_b32 s5, v255, 8
	v_mad_u32_u24 v38, v16, s82, 0
	v_ashrrev_i32_e32 v21, 5, v18
	v_lshl_add_u64 v[16:17], s[4:5], 0, v[32:33]
	v_readlane_b32 s5, v253, 56
	v_mul_lo_u32 v18, v19, s82
	v_mul_lo_u32 v32, v53, s82
	v_mul_lo_u32 v57, v52, s82
	v_mul_lo_u32 v58, v51, s82
	v_mul_lo_u32 v59, v50, s82
	v_mul_lo_u32 v60, v49, s82
	v_mul_lo_u32 v61, v48, s82
	v_mul_lo_u32 v62, v47, s82
	v_mul_lo_u32 v63, v46, s82
	v_mul_lo_u32 v64, v45, s82
	v_mul_lo_u32 v65, v44, s82
	v_mul_lo_u32 v66, v43, s82
	v_mul_lo_u32 v67, v42, s82
	v_mul_lo_u32 v68, v41, s82
	v_mul_lo_u32 v69, v40, s82
	v_mul_lo_u32 v71, v39, s82
	v_ashrrev_i32_e32 v23, 5, v23
	v_ashrrev_i32_e32 v25, 5, v25
	v_ashrrev_i32_e32 v27, 5, v27
	v_ashrrev_i32_e32 v29, 5, v29
	v_ashrrev_i32_e32 v31, 5, v31
	v_ashrrev_i32_e32 v35, 5, v35
	v_ashrrev_i32_e32 v37, 5, v37
	s_add_i32 s4, s5, s10
	v_lshl_add_u32 v22, v21, 2, v38
	v_lshl_add_u32 v24, v23, 2, v38
	v_lshl_add_u32 v26, v25, 2, v38
	v_lshl_add_u32 v28, v27, 2, v38
	v_lshl_add_u32 v30, v29, 2, v38
	v_lshl_add_u32 v34, v31, 2, v38
	v_lshl_add_u32 v36, v35, 2, v38
	v_lshl_add_u32 v38, v37, 2, v38
	s_lshl_b32 s6, s10, 6
	s_lshl_b32 s7, s5, 6
	v_lshlrev_b32_e32 v39, 10, v39
	s_lshl_b32 s8, s4, 16
	s_lshl_b32 s9, s5, 16
	v_lshlrev_b32_e32 v40, 10, v40
	v_lshlrev_b32_e32 v41, 10, v41
	v_lshlrev_b32_e32 v42, 10, v42
	v_lshlrev_b32_e32 v43, 10, v43
	v_lshlrev_b32_e32 v44, 10, v44
	v_lshlrev_b32_e32 v45, 10, v45
	v_lshlrev_b32_e32 v46, 10, v46
	v_lshlrev_b32_e32 v47, 10, v47
	v_lshlrev_b32_e32 v48, 10, v48
	v_lshlrev_b32_e32 v49, 10, v49
	v_lshlrev_b32_e32 v50, 10, v50
	v_lshlrev_b32_e32 v51, 10, v51
	v_lshlrev_b32_e32 v52, 10, v52
	v_lshlrev_b32_e32 v53, 10, v53
	v_lshlrev_b32_e32 v54, 10, v19
	v_add_u32_e32 v55, v70, v18
	v_add_u32_e32 v56, v70, v32
	v_add_u32_e32 v57, v70, v57
	v_add_u32_e32 v58, v70, v58
	v_add_u32_e32 v59, v70, v59
	v_add_u32_e32 v60, v70, v60
	v_add_u32_e32 v61, v70, v61
	v_add_u32_e32 v62, v70, v62
	v_add_u32_e32 v63, v70, v63
	v_add_u32_e32 v64, v70, v64
	v_add_u32_e32 v65, v70, v65
	v_add_u32_e32 v66, v70, v66
	v_add_u32_e32 v67, v70, v67
	v_add_u32_e32 v68, v70, v68
	v_add_u32_e32 v69, v70, v69
	v_add_u32_e32 v70, v70, v71
	v_readlane_b32 s11, v253, 37
	v_readlane_b32 s12, v253, 38
	v_readlane_b32 s13, v253, 39
	v_readlane_b32 s14, v253, 40
	v_readlane_b32 s15, v253, 41
	v_readlane_b32 s16, v253, 42
	v_readlane_b32 s17, v253, 43
	v_readlane_b32 s18, v253, 44
	v_readlane_b32 s19, v253, 45
	v_readlane_b32 s20, v253, 46
	v_readlane_b32 s21, v253, 47
	s_waitcnt vmcnt(0)
	s_branch .LBB0_230

; #define LDS_BARRIER() do { asm volatile("s_waitcnt lgkmcnt(0)" ::: "memory"); __builtin_amdgcn_s_barrier(); asm volatile("" ::: "memory"); } while (0)
;     ...
;     const int cstride = nwg ? nwg : (int)gridDim.x; bid -= wg0;
;     if (bid < 0) return;
;     if (bid < ntiles) CONVW_LOAD(bid);
;     for (int t = bid; t < ntiles; t += cstride) {
;         const int n0 = (t / nkt) * 128, k0 = (t % nkt) * 64;
; #pragma unroll
;         for (int it = 0; it < 16; ++it) { const int e = tid + 512 * it, kk = e >> 7, nn = e & 127; tile[kk * 129 + nn] = v[it]; }
;         LDS_BARRIER();
;         if (t + cstride < ntiles) CONVW_LOAD(t + cstride);
.LBB0_230:
	v_readlane_b32 s4, v253, 56
	s_waitcnt vmcnt(8)
	ds_write_b32 v55, v0
	ds_write_b32 v56, v1
	ds_write_b32 v57, v2
	ds_write_b32 v58, v3
	ds_write_b32 v59, v4
	ds_write_b32 v60, v5
	ds_write_b32 v61, v6
	ds_write_b32 v62, v7
	ds_write_b32 v63, v8
	ds_write_b32 v64, v9
	ds_write_b32 v65, v10
	ds_write_b32 v66, v11
	ds_write_b32 v67, v12
	ds_write_b32 v68, v13
	ds_write_b32 v69, v14
	ds_write_b32 v70, v15
	s_add_i32 s11, s10, s4
	s_waitcnt lgkmcnt(0)
	s_barrier
	s_cmpk_gt_i32 s11, 0x7f
	s_cselect_b64 s[4:5], -1, 0
	s_and_b64 vcc, exec, s[4:5]
	s_cbranch_vccnz .LBB0_229
	s_ashr_i32 s12, s11, 31
	s_lshr_b32 s12, s12, 28
	s_add_i32 s12, s11, s12
	s_ashr_i32 s12, s12, 4
	v_lshl_or_b32 v4, s12, 7, v20
	v_min_i32_e32 v0, 0x3ff, v4
	s_lshl_b32 s12, s12, 20
	v_ashrrev_i32_e32 v1, 31, v0
	s_sub_i32 s12, s8, s12
	v_lshl_add_u64 v[0:1], v[0:1], 2, s[0:1]
	v_add_u32_e32 v32, s12, v54
	v_lshl_add_u64 v[2:3], v[32:33], 2, v[0:1]
	v_add_u32_e32 v32, s12, v53
	global_load_dword v5, v[2:3], off
	v_lshl_add_u64 v[2:3], v[32:33], 2, v[0:1]
	v_add_u32_e32 v32, s12, v52
	global_load_dword v6, v[2:3], off
	v_lshl_add_u64 v[2:3], v[32:33], 2, v[0:1]
	v_add_u32_e32 v32, s12, v51
	global_load_dword v7, v[2:3], off
	v_lshl_add_u64 v[2:3], v[32:33], 2, v[0:1]
	v_add_u32_e32 v32, s12, v50
	global_load_dword v8, v[2:3], off
	v_lshl_add_u64 v[2:3], v[32:33], 2, v[0:1]
	v_add_u32_e32 v32, s12, v49
	global_load_dword v9, v[2:3], off
	v_lshl_add_u64 v[2:3], v[32:33], 2, v[0:1]
	v_add_u32_e32 v32, s12, v48
	global_load_dword v10, v[2:3], off
	v_lshl_add_u64 v[2:3], v[32:33], 2, v[0:1]
	v_add_u32_e32 v32, s12, v47
	global_load_dword v11, v[2:3], off
	v_lshl_add_u64 v[2:3], v[32:33], 2, v[0:1]
	v_add_u32_e32 v32, s12, v46
	global_load_dword v12, v[2:3], off
	v_lshl_add_u64 v[2:3], v[32:33], 2, v[0:1]
	v_add_u32_e32 v32, s12, v45
	global_load_dword v13, v[2:3], off
	v_lshl_add_u64 v[2:3], v[32:33], 2, v[0:1]
	v_add_u32_e32 v32, s12, v44
	global_load_dword v14, v[2:3], off
	v_lshl_add_u64 v[2:3], v[32:33], 2, v[0:1]
	v_add_u32_e32 v32, s12, v43
	global_load_dword v15, v[2:3], off
	v_lshl_add_u64 v[2:3], v[32:33], 2, v[0:1]
	v_add_u32_e32 v32, s12, v42
	global_load_dword v18, v[2:3], off
	v_lshl_add_u64 v[2:3], v[32:33], 2, v[0:1]
	v_add_u32_e32 v32, s12, v41
	global_load_dword v19, v[2:3], off
	v_lshl_add_u64 v[2:3], v[32:33], 2, v[0:1]
	v_add_u32_e32 v32, s12, v40
	global_load_dword v71, v[2:3], off
	v_lshl_add_u64 v[2:3], v[32:33], 2, v[0:1]
	v_add_u32_e32 v32, s12, v39
	v_lshl_add_u64 v[0:1], v[32:33], 2, v[0:1]
	global_load_dword v72, v[2:3], off
	global_load_dword v32, v[0:1], off
	s_movk_i32 s12, 0x400
	v_cmp_gt_i32_e32 vcc, s12, v4
	s_waitcnt vmcnt(0)
	s_nop 0
	v_cndmask_b32_e32 v0, 0, v5, vcc
	v_cndmask_b32_e32 v1, 0, v6, vcc
	v_cndmask_b32_e32 v2, 0, v7, vcc
	v_cndmask_b32_e32 v3, 0, v8, vcc
	v_cndmask_b32_e32 v4, 0, v9, vcc
	v_cndmask_b32_e32 v5, 0, v10, vcc
	v_cndmask_b32_e32 v6, 0, v11, vcc
	v_cndmask_b32_e32 v7, 0, v12, vcc
	v_cndmask_b32_e32 v8, 0, v13, vcc
	v_cndmask_b32_e32 v9, 0, v14, vcc
	v_cndmask_b32_e32 v10, 0, v15, vcc
	v_cndmask_b32_e32 v11, 0, v18, vcc
	v_cndmask_b32_e32 v12, 0, v19, vcc
	v_cndmask_b32_e32 v13, 0, v71, vcc
	v_cndmask_b32_e32 v14, 0, v72, vcc
	v_cndmask_b32_e32 v15, 0, v32, vcc
	s_branch .LBB0_229
; #define LAUNDER_V(x) asm volatile("" : "+v"(x))
; #define LAUNDER_S(x) asm volatile("" : "+s"(x))
;     float* tile = (float*)ldsb;
;     int tid = threadIdx.x; LAUNDER_V(tid); int bid = blockIdx.x; LAUNDER_S(bid);
;     const int nkt = K / 64, ntiles = (Ntot / 128) * nkt;
;     float v[16];
;     ...
;     const int cstride = nwg ? nwg : (int)gridDim.x; bid -= wg0;
;     if (bid < 0) return;
;     if (bid < ntiles) CONVW_LOAD(bid);
.LBB0_232:
	v_mov_b32_e32 v18, v192
	s_mov_b32 s0, s52
	s_add_i32 s10, s0, 0xffffff80
	s_cmpk_gt_u32 s10, 0x5f
	s_cbranch_scc1 .LBB0_237
	v_readlane_b32 s0, v255, 16
	v_readlane_b32 s1, v255, 17
	s_and_b64 s[0:1], s[0:1], exec
	s_cselect_b32 s0, 0x300000, 0
	v_readlane_b32 s36, v253, 0
	v_readlane_b32 s37, v253, 1
	s_add_u32 s0, s36, s0
	s_addc_u32 s1, s37, 0
	s_and_b32 s4, s10, 0xff
	s_mulk_i32 s4, 0xab
	s_lshr_b32 s4, s4, 11
	s_mul_i32 s5, s4, 12
	s_sub_i32 s5, s10, s5
	v_and_b32_e32 v20, 0x7f, v18
	s_and_b32 s5, s5, 0xff
	v_lshlrev_b32_e32 v19, 2, v20
	s_lshl_b32 s5, s5, 6
	v_lshl_or_b32 v32, s4, 9, v19
	v_ashrrev_i32_e32 v54, 7, v18
	v_add_u32_e32 v23, 0x200, v18
	v_lshl_add_u64 v[16:17], s[0:1], 0, v[32:33]
	v_add_lshl_u32 v32, s5, v54, 10
	v_ashrrev_i32_e32 v53, 7, v23
	v_add_u32_e32 v25, 0x400, v18
	v_lshl_add_u64 v[0:1], v[32:33], 2, v[16:17]
	v_add_lshl_u32 v32, s5, v53, 10
	v_ashrrev_i32_e32 v52, 7, v25
	v_add_u32_e32 v27, 0x600, v18
	v_lshl_add_u64 v[2:3], v[32:33], 2, v[16:17]
	v_add_lshl_u32 v32, s5, v52, 10
	v_ashrrev_i32_e32 v51, 7, v27
	v_add_u32_e32 v29, 0x800, v18
	global_load_dword v0, v[0:1], off
	v_ashrrev_i32_e32 v50, 7, v29
	global_load_dword v1, v[2:3], off
	v_lshl_add_u64 v[2:3], v[32:33], 2, v[16:17]
	v_add_lshl_u32 v32, s5, v51, 10
	v_add_u32_e32 v31, 0xa00, v18
	v_lshl_add_u64 v[4:5], v[32:33], 2, v[16:17]
	v_add_lshl_u32 v32, s5, v50, 10
	v_ashrrev_i32_e32 v49, 7, v31
	v_add_u32_e32 v35, 0xc00, v18
	global_load_dword v2, v[2:3], off
	v_ashrrev_i32_e32 v48, 7, v35
	global_load_dword v3, v[4:5], off
	v_lshl_add_u64 v[4:5], v[32:33], 2, v[16:17]
	v_add_lshl_u32 v32, s5, v49, 10
	v_add_u32_e32 v37, 0xe00, v18
	v_lshl_add_u64 v[6:7], v[32:33], 2, v[16:17]
	v_add_lshl_u32 v32, s5, v48, 10
	v_ashrrev_i32_e32 v47, 7, v37
	global_load_dword v4, v[4:5], off
	v_add_u32_e32 v19, 0, v19
	global_load_dword v5, v[6:7], off
	v_lshl_add_u64 v[6:7], v[32:33], 2, v[16:17]
	v_add_lshl_u32 v32, s5, v47, 10
	v_lshl_add_u64 v[8:9], v[32:33], 2, v[16:17]
	global_load_dword v6, v[6:7], off
	v_ashrrev_i32_e32 v21, 5, v18
	global_load_dword v7, v[8:9], off
	v_add_u32_e32 v8, 0x1000, v18
	v_ashrrev_i32_e32 v46, 7, v8
	v_add_lshl_u32 v32, s5, v46, 10
	v_lshl_add_u64 v[8:9], v[32:33], 2, v[16:17]
	global_load_dword v8, v[8:9], off
	v_add_u32_e32 v9, 0x1200, v18
	v_ashrrev_i32_e32 v45, 7, v9
	v_add_lshl_u32 v32, s5, v45, 10
	v_lshl_add_u64 v[10:11], v[32:33], 2, v[16:17]
	global_load_dword v9, v[10:11], off
	v_add_u32_e32 v10, 0x1400, v18
	v_ashrrev_i32_e32 v44, 7, v10
	v_add_lshl_u32 v32, s5, v44, 10
	v_lshl_add_u64 v[10:11], v[32:33], 2, v[16:17]
	global_load_dword v10, v[10:11], off
	v_add_u32_e32 v11, 0x1600, v18
	v_ashrrev_i32_e32 v43, 7, v11
	v_add_lshl_u32 v32, s5, v43, 10
	v_lshl_add_u64 v[12:13], v[32:33], 2, v[16:17]
	global_load_dword v11, v[12:13], off
	v_add_u32_e32 v12, 0x1800, v18
	v_ashrrev_i32_e32 v42, 7, v12
	v_add_lshl_u32 v32, s5, v42, 10
	v_lshl_add_u64 v[12:13], v[32:33], 2, v[16:17]
	global_load_dword v12, v[12:13], off
	v_add_u32_e32 v13, 0x1a00, v18
	v_ashrrev_i32_e32 v41, 7, v13
	v_add_lshl_u32 v32, s5, v41, 10
	v_lshl_add_u64 v[14:15], v[32:33], 2, v[16:17]
	global_load_dword v13, v[14:15], off
	v_add_u32_e32 v14, 0x1c00, v18
	v_ashrrev_i32_e32 v40, 7, v14
	v_add_lshl_u32 v32, s5, v40, 10
	v_lshl_add_u64 v[14:15], v[32:33], 2, v[16:17]
	global_load_dword v14, v[14:15], off
	v_add_u32_e32 v15, 0x1e00, v18
	v_ashrrev_i32_e32 v39, 7, v15
	v_add_lshl_u32 v32, s5, v39, 10
	v_lshl_add_u64 v[16:17], v[32:33], 2, v[16:17]
	global_load_dword v15, v[16:17], off
	v_lshlrev_b32_e32 v16, 1, v18
	v_and_b32_e32 v16, 62, v16
	v_readlane_b32 s4, v255, 9
	v_lshlrev_b32_e32 v32, 1, v16
	v_readlane_b32 s5, v255, 10
	v_mad_u32_u24 v38, v16, s82, 0
	v_mul_lo_u32 v18, v54, s82
	v_lshl_add_u64 v[16:17], s[4:5], 0, v[32:33]
	v_readlane_b32 s5, v253, 56
	v_mul_lo_u32 v32, v53, s82
	v_mul_lo_u32 v57, v52, s82
	v_mul_lo_u32 v58, v51, s82
	v_mul_lo_u32 v59, v50, s82
	v_mul_lo_u32 v60, v49, s82
	v_mul_lo_u32 v61, v48, s82
	v_mul_lo_u32 v62, v47, s82
	v_mul_lo_u32 v63, v46, s82
	v_mul_lo_u32 v64, v45, s82
	v_mul_lo_u32 v65, v44, s82
	v_mul_lo_u32 v66, v43, s82
	v_mul_lo_u32 v67, v42, s82
	v_mul_lo_u32 v68, v41, s82
	v_mul_lo_u32 v69, v40, s82
	v_mul_lo_u32 v70, v39, s82
	v_ashrrev_i32_e32 v23, 5, v23
	v_ashrrev_i32_e32 v25, 5, v25
	v_ashrrev_i32_e32 v27, 5, v27
	v_ashrrev_i32_e32 v29, 5, v29
	v_ashrrev_i32_e32 v31, 5, v31
	v_ashrrev_i32_e32 v35, 5, v35
	v_ashrrev_i32_e32 v37, 5, v37
	s_add_i32 s4, s5, s10
	v_lshl_add_u32 v22, v21, 2, v38
	v_lshl_add_u32 v24, v23, 2, v38
	v_lshl_add_u32 v26, v25, 2, v38
	v_lshl_add_u32 v28, v27, 2, v38
	v_lshl_add_u32 v30, v29, 2, v38
	v_lshl_add_u32 v34, v31, 2, v38
	v_lshl_add_u32 v36, v35, 2, v38
	v_lshl_add_u32 v38, v37, 2, v38
	s_lshl_b32 s6, s10, 6
	s_lshl_b32 s7, s5, 6
	v_lshlrev_b32_e32 v39, 10, v39
	s_lshl_b32 s8, s4, 16
	s_lshl_b32 s9, s5, 16
	v_lshlrev_b32_e32 v40, 10, v40
	v_lshlrev_b32_e32 v41, 10, v41
	v_lshlrev_b32_e32 v42, 10, v42
	v_lshlrev_b32_e32 v43, 10, v43
	v_lshlrev_b32_e32 v44, 10, v44
	v_lshlrev_b32_e32 v45, 10, v45
	v_lshlrev_b32_e32 v46, 10, v46
	v_lshlrev_b32_e32 v47, 10, v47
	v_lshlrev_b32_e32 v48, 10, v48
	v_lshlrev_b32_e32 v49, 10, v49
	v_lshlrev_b32_e32 v50, 10, v50
	v_lshlrev_b32_e32 v51, 10, v51
	v_lshlrev_b32_e32 v52, 10, v52
	v_lshlrev_b32_e32 v53, 10, v53
	v_lshlrev_b32_e32 v54, 10, v54
	v_add_u32_e32 v55, v19, v18
	v_add_u32_e32 v56, v19, v32
	v_add_u32_e32 v57, v19, v57
	v_add_u32_e32 v58, v19, v58
	v_add_u32_e32 v59, v19, v59
	v_add_u32_e32 v60, v19, v60
	v_add_u32_e32 v61, v19, v61
	v_add_u32_e32 v62, v19, v62
	v_add_u32_e32 v63, v19, v63
	v_add_u32_e32 v64, v19, v64
	v_add_u32_e32 v65, v19, v65
	v_add_u32_e32 v66, v19, v66
	v_add_u32_e32 v67, v19, v67
	v_add_u32_e32 v68, v19, v68
	v_add_u32_e32 v69, v19, v69
	v_add_u32_e32 v70, v19, v70
	v_readlane_b32 s38, v253, 2
	v_readlane_b32 s39, v253, 3
	v_readlane_b32 s40, v253, 4
	v_readlane_b32 s41, v253, 5
	v_readlane_b32 s42, v253, 6
	v_readlane_b32 s43, v253, 7
	v_readlane_b32 s44, v253, 8
	v_readlane_b32 s45, v253, 9
	v_readlane_b32 s46, v253, 10
	v_readlane_b32 s47, v253, 11
	v_readlane_b32 s48, v253, 12
	v_readlane_b32 s49, v253, 13
	v_readlane_b32 s50, v253, 14
	v_readlane_b32 s51, v253, 15
	s_waitcnt vmcnt(0)
	s_branch .LBB0_235

; #define LDS_BARRIER() do { asm volatile("s_waitcnt lgkmcnt(0)" ::: "memory"); __builtin_amdgcn_s_barrier(); asm volatile("" ::: "memory"); } while (0)
;     ...
;     const int cstride = nwg ? nwg : (int)gridDim.x; bid -= wg0;
;     if (bid < 0) return;
;     if (bid < ntiles) CONVW_LOAD(bid);
;     for (int t = bid; t < ntiles; t += cstride) {
;         const int n0 = (t / nkt) * 128, k0 = (t % nkt) * 64;
; #pragma unroll
;         for (int it = 0; it < 16; ++it) { const int e = tid + 512 * it, kk = e >> 7, nn = e & 127; tile[kk * 129 + nn] = v[it]; }
;         LDS_BARRIER();
;         if (t + cstride < ntiles) CONVW_LOAD(t + cstride);
.LBB0_235:
	v_readlane_b32 s4, v253, 56
	s_waitcnt vmcnt(8)
	ds_write_b32 v55, v0
	ds_write_b32 v56, v1
	ds_write_b32 v57, v2
	ds_write_b32 v58, v3
	ds_write_b32 v59, v4
	ds_write_b32 v60, v5
	ds_write_b32 v61, v6
	ds_write_b32 v62, v7
	ds_write_b32 v63, v8
	ds_write_b32 v64, v9
	ds_write_b32 v65, v10
	ds_write_b32 v66, v11
	ds_write_b32 v67, v12
	ds_write_b32 v68, v13
	ds_write_b32 v69, v14
	ds_write_b32 v70, v15
	s_add_i32 s11, s10, s4
	s_waitcnt lgkmcnt(0)
	s_barrier
	s_cmpk_gt_i32 s11, 0x5f
	s_cselect_b64 s[4:5], -1, 0
	s_and_b64 vcc, exec, s[4:5]
	s_cbranch_vccnz .LBB0_234
	s_mul_hi_i32 s12, s11, 0x2aaaaaab
	s_lshr_b32 s13, s12, 31
	s_ashr_i32 s12, s12, 1
	s_add_i32 s12, s12, s13
	v_lshl_or_b32 v4, s12, 7, v20
	v_min_i32_e32 v0, 0x3ff, v4
	s_mul_i32 s12, s12, 0xfff40000
	v_ashrrev_i32_e32 v1, 31, v0
	s_add_i32 s12, s12, s8
	v_lshl_add_u64 v[0:1], v[0:1], 2, s[0:1]
	v_add_u32_e32 v32, s12, v54
	v_lshl_add_u64 v[2:3], v[32:33], 2, v[0:1]
	v_add_u32_e32 v32, s12, v53
	global_load_dword v5, v[2:3], off
	v_lshl_add_u64 v[2:3], v[32:33], 2, v[0:1]
	v_add_u32_e32 v32, s12, v52
	global_load_dword v6, v[2:3], off
	v_lshl_add_u64 v[2:3], v[32:33], 2, v[0:1]
	v_add_u32_e32 v32, s12, v51
	global_load_dword v7, v[2:3], off
	v_lshl_add_u64 v[2:3], v[32:33], 2, v[0:1]
	v_add_u32_e32 v32, s12, v50
	global_load_dword v8, v[2:3], off
	v_lshl_add_u64 v[2:3], v[32:33], 2, v[0:1]
	v_add_u32_e32 v32, s12, v49
	global_load_dword v9, v[2:3], off
	v_lshl_add_u64 v[2:3], v[32:33], 2, v[0:1]
	v_add_u32_e32 v32, s12, v48
	global_load_dword v10, v[2:3], off
	v_lshl_add_u64 v[2:3], v[32:33], 2, v[0:1]
	v_add_u32_e32 v32, s12, v47
	global_load_dword v11, v[2:3], off
	v_lshl_add_u64 v[2:3], v[32:33], 2, v[0:1]
	v_add_u32_e32 v32, s12, v46
	global_load_dword v12, v[2:3], off
	v_lshl_add_u64 v[2:3], v[32:33], 2, v[0:1]
	v_add_u32_e32 v32, s12, v45
	global_load_dword v13, v[2:3], off
	v_lshl_add_u64 v[2:3], v[32:33], 2, v[0:1]
	v_add_u32_e32 v32, s12, v44
	global_load_dword v14, v[2:3], off
	v_lshl_add_u64 v[2:3], v[32:33], 2, v[0:1]
	v_add_u32_e32 v32, s12, v43
	global_load_dword v15, v[2:3], off
	v_lshl_add_u64 v[2:3], v[32:33], 2, v[0:1]
	v_add_u32_e32 v32, s12, v42
	global_load_dword v18, v[2:3], off
	v_lshl_add_u64 v[2:3], v[32:33], 2, v[0:1]
	v_add_u32_e32 v32, s12, v41
	global_load_dword v19, v[2:3], off
	v_lshl_add_u64 v[2:3], v[32:33], 2, v[0:1]
	v_add_u32_e32 v32, s12, v40
	global_load_dword v71, v[2:3], off
	v_lshl_add_u64 v[2:3], v[32:33], 2, v[0:1]
	v_add_u32_e32 v32, s12, v39
	v_lshl_add_u64 v[0:1], v[32:33], 2, v[0:1]
	global_load_dword v72, v[2:3], off
	global_load_dword v32, v[0:1], off
	s_movk_i32 s12, 0x400
	v_cmp_gt_i32_e32 vcc, s12, v4
	s_waitcnt vmcnt(0)
	s_nop 0
	v_cndmask_b32_e32 v0, 0, v5, vcc
	v_cndmask_b32_e32 v1, 0, v6, vcc
	v_cndmask_b32_e32 v2, 0, v7, vcc
	v_cndmask_b32_e32 v3, 0, v8, vcc
	v_cndmask_b32_e32 v4, 0, v9, vcc
	v_cndmask_b32_e32 v5, 0, v10, vcc
	v_cndmask_b32_e32 v6, 0, v11, vcc
	v_cndmask_b32_e32 v7, 0, v12, vcc
	v_cndmask_b32_e32 v8, 0, v13, vcc
	v_cndmask_b32_e32 v9, 0, v14, vcc
	v_cndmask_b32_e32 v10, 0, v15, vcc
	v_cndmask_b32_e32 v11, 0, v18, vcc
	v_cndmask_b32_e32 v12, 0, v19, vcc
	v_cndmask_b32_e32 v13, 0, v71, vcc
	v_cndmask_b32_e32 v14, 0, v72, vcc
	v_cndmask_b32_e32 v15, 0, v32, vcc
	s_branch .LBB0_234
; #define LAUNDER_V(x) asm volatile("" : "+v"(x))
; #define LAUNDER_S(x) asm volatile("" : "+s"(x))
;     float* tile = (float*)ldsb;
;     int tid = threadIdx.x; LAUNDER_V(tid); int bid = blockIdx.x; LAUNDER_S(bid);
;     const int nkt = K / 64, ntiles = (Ntot / 128) * nkt;
;     float v[16];
;     ...
;     const int cstride = nwg ? nwg : (int)gridDim.x; bid -= wg0;
;     if (bid < 0) return;
;     if (bid < ntiles) CONVW_LOAD(bid);
.LBB0_237:
	v_mov_b32_e32 v18, v192
	s_mov_b32 s4, s52
	s_and_b32 s0, s4, 0xffffff80
	s_cmpk_lg_i32 s0, 0x80
	s_cbranch_scc1 .LBB0_242
	v_readlane_b32 s8, v253, 0
	s_lshl_b32 s0, s3, 2
	v_readlane_b32 s10, v253, 2
	v_readlane_b32 s9, v253, 1
	v_readlane_b32 s11, v253, 3
	s_add_u32 s0, s10, s0
	s_addc_u32 s1, s11, 0
	s_add_i32 s9, s4, 0xffffff80
	s_lshl_b32 s3, s9, 3
	s_and_b32 s3, s3, 0x380
	v_and_b32_e32 v20, 0x7f, v18
	s_lshl_b32 s4, s4, 6
	v_or_b32_e32 v0, s3, v20
	s_and_b32 s4, s4, 0x3c0
	v_lshlrev_b32_e32 v32, 2, v0
	v_ashrrev_i32_e32 v19, 7, v18
	v_add_u32_e32 v23, 0x200, v18
	v_lshl_add_u64 v[16:17], s[0:1], 0, v[32:33]
	v_add_lshl_u32 v32, s4, v19, 10
	v_ashrrev_i32_e32 v53, 7, v23
	v_add_u32_e32 v25, 0x400, v18
	v_lshl_add_u64 v[0:1], v[32:33], 2, v[16:17]
	v_add_lshl_u32 v32, s4, v53, 10
	v_ashrrev_i32_e32 v52, 7, v25
	v_add_u32_e32 v27, 0x600, v18
	v_lshl_add_u64 v[2:3], v[32:33], 2, v[16:17]
	v_add_lshl_u32 v32, s4, v52, 10
	v_ashrrev_i32_e32 v51, 7, v27
	v_add_u32_e32 v29, 0x800, v18
	global_load_dword v0, v[0:1], off
	v_ashrrev_i32_e32 v50, 7, v29
	global_load_dword v1, v[2:3], off
	v_lshl_add_u64 v[2:3], v[32:33], 2, v[16:17]
	v_add_lshl_u32 v32, s4, v51, 10
	v_add_u32_e32 v31, 0xa00, v18
	v_lshl_add_u64 v[4:5], v[32:33], 2, v[16:17]
	v_add_lshl_u32 v32, s4, v50, 10
	v_ashrrev_i32_e32 v49, 7, v31
	v_add_u32_e32 v35, 0xc00, v18
	global_load_dword v2, v[2:3], off
	v_ashrrev_i32_e32 v48, 7, v35
	global_load_dword v3, v[4:5], off
	v_lshl_add_u64 v[4:5], v[32:33], 2, v[16:17]
	v_add_lshl_u32 v32, s4, v49, 10
	v_add_u32_e32 v37, 0xe00, v18
	v_lshl_add_u64 v[6:7], v[32:33], 2, v[16:17]
	v_add_lshl_u32 v32, s4, v48, 10
	v_ashrrev_i32_e32 v47, 7, v37
	global_load_dword v4, v[4:5], off
	v_lshl_add_u32 v70, v20, 2, 0
	global_load_dword v5, v[6:7], off
	v_lshl_add_u64 v[6:7], v[32:33], 2, v[16:17]
	v_add_lshl_u32 v32, s4, v47, 10
	v_lshl_add_u64 v[8:9], v[32:33], 2, v[16:17]
	global_load_dword v6, v[6:7], off
	v_ashrrev_i32_e32 v21, 5, v18
	global_load_dword v7, v[8:9], off
	v_add_u32_e32 v8, 0x1000, v18
	v_ashrrev_i32_e32 v46, 7, v8
	v_add_lshl_u32 v32, s4, v46, 10
	v_lshl_add_u64 v[8:9], v[32:33], 2, v[16:17]
	global_load_dword v8, v[8:9], off
	v_add_u32_e32 v9, 0x1200, v18
	v_ashrrev_i32_e32 v45, 7, v9
	v_add_lshl_u32 v32, s4, v45, 10
	v_lshl_add_u64 v[10:11], v[32:33], 2, v[16:17]
	global_load_dword v9, v[10:11], off
	v_add_u32_e32 v10, 0x1400, v18
	v_ashrrev_i32_e32 v44, 7, v10
	v_add_lshl_u32 v32, s4, v44, 10
	v_lshl_add_u64 v[10:11], v[32:33], 2, v[16:17]
	global_load_dword v10, v[10:11], off
	v_add_u32_e32 v11, 0x1600, v18
	v_ashrrev_i32_e32 v43, 7, v11
	v_add_lshl_u32 v32, s4, v43, 10
	v_lshl_add_u64 v[12:13], v[32:33], 2, v[16:17]
	global_load_dword v11, v[12:13], off
	v_add_u32_e32 v12, 0x1800, v18
	v_ashrrev_i32_e32 v42, 7, v12
	v_add_lshl_u32 v32, s4, v42, 10
	v_lshl_add_u64 v[12:13], v[32:33], 2, v[16:17]
	global_load_dword v12, v[12:13], off
	v_add_u32_e32 v13, 0x1a00, v18
	v_ashrrev_i32_e32 v41, 7, v13
	v_add_lshl_u32 v32, s4, v41, 10
	v_lshl_add_u64 v[14:15], v[32:33], 2, v[16:17]
	global_load_dword v13, v[14:15], off
	v_add_u32_e32 v14, 0x1c00, v18
	v_ashrrev_i32_e32 v40, 7, v14
	v_add_lshl_u32 v32, s4, v40, 10
	v_lshl_add_u64 v[14:15], v[32:33], 2, v[16:17]
	global_load_dword v14, v[14:15], off
	v_add_u32_e32 v15, 0x1e00, v18
	v_ashrrev_i32_e32 v39, 7, v15
	v_add_lshl_u32 v32, s4, v39, 10
	v_lshl_add_u64 v[16:17], v[32:33], 2, v[16:17]
	global_load_dword v15, v[16:17], off
	v_lshlrev_b32_e32 v16, 1, v18
	v_and_b32_e32 v16, 62, v16
	v_readlane_b32 s4, v255, 11
	v_lshlrev_b32_e32 v32, 1, v16
	v_readlane_b32 s5, v255, 12
	v_mad_u32_u24 v38, v16, s82, 0
	v_mul_lo_u32 v18, v19, s82
	v_lshl_add_u64 v[16:17], s[4:5], 0, v[32:33]
	v_readlane_b32 s5, v253, 56
	v_mul_lo_u32 v32, v53, s82
	v_mul_lo_u32 v57, v52, s82
	v_mul_lo_u32 v58, v51, s82
	v_mul_lo_u32 v59, v50, s82
	v_mul_lo_u32 v60, v49, s82
	v_mul_lo_u32 v61, v48, s82
	v_mul_lo_u32 v62, v47, s82
	v_mul_lo_u32 v63, v46, s82
	v_mul_lo_u32 v64, v45, s82
	v_mul_lo_u32 v65, v44, s82
	v_mul_lo_u32 v66, v43, s82
	v_mul_lo_u32 v67, v42, s82
	v_mul_lo_u32 v68, v41, s82
	v_mul_lo_u32 v69, v40, s82
	v_mul_lo_u32 v71, v39, s82
	v_ashrrev_i32_e32 v23, 5, v23
	v_ashrrev_i32_e32 v25, 5, v25
	v_ashrrev_i32_e32 v27, 5, v27
	v_ashrrev_i32_e32 v29, 5, v29
	v_ashrrev_i32_e32 v31, 5, v31
	v_ashrrev_i32_e32 v35, 5, v35
	v_ashrrev_i32_e32 v37, 5, v37
	s_add_i32 s4, s5, s9
	v_lshl_add_u32 v22, v21, 2, v38
	v_lshl_add_u32 v24, v23, 2, v38
	v_lshl_add_u32 v26, v25, 2, v38
	v_lshl_add_u32 v28, v27, 2, v38
	v_lshl_add_u32 v30, v29, 2, v38
	v_lshl_add_u32 v34, v31, 2, v38
	v_lshl_add_u32 v36, v35, 2, v38
	v_lshl_add_u32 v38, v37, 2, v38
	s_lshl_b32 s3, s9, 6
	s_lshl_b32 s6, s5, 6
	v_lshlrev_b32_e32 v39, 10, v39
	s_lshl_b32 s7, s4, 16
	s_lshl_b32 s8, s5, 16
	v_lshlrev_b32_e32 v40, 10, v40
	v_lshlrev_b32_e32 v41, 10, v41
	v_lshlrev_b32_e32 v42, 10, v42
	v_lshlrev_b32_e32 v43, 10, v43
	v_lshlrev_b32_e32 v44, 10, v44
	v_lshlrev_b32_e32 v45, 10, v45
	v_lshlrev_b32_e32 v46, 10, v46
	v_lshlrev_b32_e32 v47, 10, v47
	v_lshlrev_b32_e32 v48, 10, v48
	v_lshlrev_b32_e32 v49, 10, v49
	v_lshlrev_b32_e32 v50, 10, v50
	v_lshlrev_b32_e32 v51, 10, v51
	v_lshlrev_b32_e32 v52, 10, v52
	v_lshlrev_b32_e32 v53, 10, v53
	v_lshlrev_b32_e32 v54, 10, v19
	v_add_u32_e32 v55, v70, v18
	v_add_u32_e32 v56, v70, v32
	v_add_u32_e32 v57, v70, v57
	v_add_u32_e32 v58, v70, v58
	v_add_u32_e32 v59, v70, v59
	v_add_u32_e32 v60, v70, v60
	v_add_u32_e32 v61, v70, v61
	v_add_u32_e32 v62, v70, v62
	v_add_u32_e32 v63, v70, v63
	v_add_u32_e32 v64, v70, v64
	v_add_u32_e32 v65, v70, v65
	v_add_u32_e32 v66, v70, v66
	v_add_u32_e32 v67, v70, v67
	v_add_u32_e32 v68, v70, v68
	v_add_u32_e32 v69, v70, v69
	v_add_u32_e32 v70, v70, v71
	v_readlane_b32 s12, v253, 4
	v_readlane_b32 s13, v253, 5
	v_readlane_b32 s14, v253, 6
	v_readlane_b32 s15, v253, 7
	v_readlane_b32 s16, v253, 8
	v_readlane_b32 s17, v253, 9
	v_readlane_b32 s18, v253, 10
	v_readlane_b32 s19, v253, 11
	v_readlane_b32 s20, v253, 12
	v_readlane_b32 s21, v253, 13
	v_readlane_b32 s22, v253, 14
	v_readlane_b32 s23, v253, 15
	s_waitcnt vmcnt(0)
	s_branch .LBB0_240

; #define LDS_BARRIER() do { asm volatile("s_waitcnt lgkmcnt(0)" ::: "memory"); __builtin_amdgcn_s_barrier(); asm volatile("" ::: "memory"); } while (0)
;     ...
;     const int cstride = nwg ? nwg : (int)gridDim.x; bid -= wg0;
;     if (bid < 0) return;
;     if (bid < ntiles) CONVW_LOAD(bid);
;     for (int t = bid; t < ntiles; t += cstride) {
;         const int n0 = (t / nkt) * 128, k0 = (t % nkt) * 64;
; #pragma unroll
;         for (int it = 0; it < 16; ++it) { const int e = tid + 512 * it, kk = e >> 7, nn = e & 127; tile[kk * 129 + nn] = v[it]; }
;         LDS_BARRIER();
;         if (t + cstride < ntiles) CONVW_LOAD(t + cstride);
.LBB0_240:
	v_readlane_b32 s4, v253, 56
	s_waitcnt vmcnt(8)
	ds_write_b32 v55, v0
	ds_write_b32 v56, v1
	ds_write_b32 v57, v2
	ds_write_b32 v58, v3
	ds_write_b32 v59, v4
	ds_write_b32 v60, v5
	ds_write_b32 v61, v6
	ds_write_b32 v62, v7
	ds_write_b32 v63, v8
	ds_write_b32 v64, v9
	ds_write_b32 v65, v10
	ds_write_b32 v66, v11
	ds_write_b32 v67, v12
	ds_write_b32 v68, v13
	ds_write_b32 v69, v14
	ds_write_b32 v70, v15
	s_add_i32 s10, s9, s4
	s_waitcnt lgkmcnt(0)
	s_barrier
	s_cmpk_gt_i32 s10, 0x7f
	s_cselect_b64 s[4:5], -1, 0
	s_and_b64 vcc, exec, s[4:5]
	s_cbranch_vccnz .LBB0_239
	s_ashr_i32 s11, s10, 31
	s_lshr_b32 s11, s11, 28
	s_add_i32 s11, s10, s11
	s_ashr_i32 s11, s11, 4
	v_lshl_or_b32 v4, s11, 7, v20
	v_min_i32_e32 v0, 0x3ff, v4
	s_lshl_b32 s11, s11, 20
	v_ashrrev_i32_e32 v1, 31, v0
	s_sub_i32 s11, s7, s11
	v_lshl_add_u64 v[0:1], v[0:1], 2, s[0:1]
	v_add_u32_e32 v32, s11, v54
	v_lshl_add_u64 v[2:3], v[32:33], 2, v[0:1]
	v_add_u32_e32 v32, s11, v53
	global_load_dword v5, v[2:3], off
	v_lshl_add_u64 v[2:3], v[32:33], 2, v[0:1]
	v_add_u32_e32 v32, s11, v52
	global_load_dword v6, v[2:3], off
	v_lshl_add_u64 v[2:3], v[32:33], 2, v[0:1]
	v_add_u32_e32 v32, s11, v51
	global_load_dword v7, v[2:3], off
	v_lshl_add_u64 v[2:3], v[32:33], 2, v[0:1]
	v_add_u32_e32 v32, s11, v50
	global_load_dword v8, v[2:3], off
	v_lshl_add_u64 v[2:3], v[32:33], 2, v[0:1]
	v_add_u32_e32 v32, s11, v49
	global_load_dword v9, v[2:3], off
	v_lshl_add_u64 v[2:3], v[32:33], 2, v[0:1]
	v_add_u32_e32 v32, s11, v48
	global_load_dword v10, v[2:3], off
	v_lshl_add_u64 v[2:3], v[32:33], 2, v[0:1]
	v_add_u32_e32 v32, s11, v47
	global_load_dword v11, v[2:3], off
	v_lshl_add_u64 v[2:3], v[32:33], 2, v[0:1]
	v_add_u32_e32 v32, s11, v46
	global_load_dword v12, v[2:3], off
	v_lshl_add_u64 v[2:3], v[32:33], 2, v[0:1]
	v_add_u32_e32 v32, s11, v45
	global_load_dword v13, v[2:3], off
	v_lshl_add_u64 v[2:3], v[32:33], 2, v[0:1]
	v_add_u32_e32 v32, s11, v44
	global_load_dword v14, v[2:3], off
	v_lshl_add_u64 v[2:3], v[32:33], 2, v[0:1]
	v_add_u32_e32 v32, s11, v43
	global_load_dword v15, v[2:3], off
	v_lshl_add_u64 v[2:3], v[32:33], 2, v[0:1]
	v_add_u32_e32 v32, s11, v42
	global_load_dword v18, v[2:3], off
	v_lshl_add_u64 v[2:3], v[32:33], 2, v[0:1]
	v_add_u32_e32 v32, s11, v41
	global_load_dword v19, v[2:3], off
	v_lshl_add_u64 v[2:3], v[32:33], 2, v[0:1]
	v_add_u32_e32 v32, s11, v40
	global_load_dword v71, v[2:3], off
	v_lshl_add_u64 v[2:3], v[32:33], 2, v[0:1]
	v_add_u32_e32 v32, s11, v39
	v_lshl_add_u64 v[0:1], v[32:33], 2, v[0:1]
	global_load_dword v72, v[2:3], off
	global_load_dword v32, v[0:1], off
	s_movk_i32 s11, 0x400
	v_cmp_gt_i32_e32 vcc, s11, v4
	s_waitcnt vmcnt(0)
	s_nop 0
	v_cndmask_b32_e32 v0, 0, v5, vcc
	v_cndmask_b32_e32 v1, 0, v6, vcc
	v_cndmask_b32_e32 v2, 0, v7, vcc
	v_cndmask_b32_e32 v3, 0, v8, vcc
	v_cndmask_b32_e32 v4, 0, v9, vcc
	v_cndmask_b32_e32 v5, 0, v10, vcc
	v_cndmask_b32_e32 v6, 0, v11, vcc
	v_cndmask_b32_e32 v7, 0, v12, vcc
	v_cndmask_b32_e32 v8, 0, v13, vcc
	v_cndmask_b32_e32 v9, 0, v14, vcc
	v_cndmask_b32_e32 v10, 0, v15, vcc
	v_cndmask_b32_e32 v11, 0, v18, vcc
	v_cndmask_b32_e32 v12, 0, v19, vcc
	v_cndmask_b32_e32 v13, 0, v71, vcc
	v_cndmask_b32_e32 v14, 0, v72, vcc
	v_cndmask_b32_e32 v15, 0, v32, vcc
	s_branch .LBB0_239

; #define LAUNDER_V(x) asm volatile("" : "+v"(x))
; #define LAUNDER_S(x) asm volatile("" : "+s"(x))
;     float* tile = (float*)ldsb;
;     int tid = threadIdx.x; LAUNDER_V(tid); int bid = blockIdx.x; LAUNDER_S(bid);
;     const int nkt = K / 64, ntiles = (Ntot / 128) * nkt;
;     float v[16];
;     ...
;     const int cstride = nwg ? nwg : (int)gridDim.x; bid -= wg0;
;     if (bid < 0) return;
;     if (bid < ntiles) CONVW_LOAD(bid);
; __global__ void __launch_bounds__(512, 2) fwd_mega(Params p) {
;     ...
;                     if (ck == 3 && ci >= 3 && ci <= 5) continue;
;                     conv_w(src, ldsrc, coloff, nvalid, Ntot, K, dst, inter, lds);
.LBB0_839:
	s_add_i32 s30, s2, -3
	s_cmp_lt_u32 s30, 3
	s_cselect_b64 s[30:31], -1, 0
	s_and_b64 s[30:31], s[6:7], s[30:31]
	s_and_b64 vcc, exec, s[30:31]
	s_cbranch_vccnz .LBB0_802
	s_waitcnt vmcnt(0)
	v_mov_b32_e32 v11, v192
	s_mov_b32 s70, s52
	s_lshr_b32 s30, s55, 6
	s_mul_i32 s31, s30, s57
	s_cmp_gt_i32 s70, -1
	s_cselect_b64 s[68:69], -1, 0
	s_cmp_lt_i32 s70, s31
	s_cselect_b64 s[72:73], -1, 0
	s_and_b64 s[68:69], s[68:69], s[72:73]
	s_andn2_b64 vcc, exec, s[68:69]
	s_cbranch_vccnz .LBB0_802
	v_cvt_f32_u32_e32 v0, s30
	s_and_b32 s57, s70, 0xffff
	v_cvt_f32_u32_e32 v1, s57
	v_and_b32_e32 v20, 0x7f, v11
	v_rcp_iflag_f32_e32 v36, v0
	v_ashrrev_i32_e32 v62, 7, v11
	v_add_u32_e32 v23, 0x200, v11
	v_ashrrev_i32_e32 v61, 7, v23
	v_mul_f32_e32 v2, v1, v36
	v_trunc_f32_e32 v2, v2
	v_cvt_u32_f32_e32 v3, v2
	v_fma_f32 v1, -v2, v0, v1
	v_cmp_ge_f32_e64 s[68:69], |v1|, v0
	s_cmp_lg_u64 s[68:69], 0
	v_readfirstlane_b32 s57, v3
	s_addc_u32 s59, s57, 0
	s_and_b32 s68, s59, 0xffff
	s_add_i32 s57, s54, -1
	s_mul_i32 s59, s59, s30
	v_lshl_or_b32 v10, s68, 7, v20
	s_sub_i32 s59, s70, s59
	v_min_u32_e32 v0, s57, v10
	s_lshl_b32 s59, s59, 6
	v_lshlrev_b32_e32 v32, 2, v0
	s_and_b32 s59, s59, 0xffc0
	v_lshl_add_u64 v[0:1], s[4:5], 0, v[32:33]
	s_lshl_b64 s[26:27], s[26:27], 2
	v_lshl_add_u64 v[8:9], v[0:1], 0, s[26:27]
	v_add_u32_e32 v0, s59, v62
	v_add_u32_e32 v25, 0x400, v11
	v_mul_lo_u32 v32, v0, s56
	v_add_u32_e32 v2, s59, v61
	v_ashrrev_i32_e32 v60, 7, v25
	v_add_u32_e32 v27, 0x600, v11
	v_lshl_add_u64 v[0:1], v[32:33], 2, v[8:9]
	v_mul_lo_u32 v32, v2, s56
	v_add_u32_e32 v4, s59, v60
	v_ashrrev_i32_e32 v59, 7, v27
	v_add_u32_e32 v29, 0x800, v11
	v_lshl_add_u64 v[2:3], v[32:33], 2, v[8:9]
	v_mul_lo_u32 v32, v4, s56
	v_add_u32_e32 v6, s59, v59
	v_ashrrev_i32_e32 v58, 7, v29
	v_add_u32_e32 v31, 0xa00, v11
	v_lshl_add_u64 v[4:5], v[32:33], 2, v[8:9]
	v_mul_lo_u32 v32, v6, s56
	v_add_u32_e32 v12, s59, v58
	v_ashrrev_i32_e32 v57, 7, v31
	v_add_u32_e32 v35, 0xc00, v11
	v_lshl_add_u64 v[6:7], v[32:33], 2, v[8:9]
	v_mul_lo_u32 v32, v12, s56
	v_add_u32_e32 v14, s59, v57
	v_ashrrev_i32_e32 v56, 7, v35
	v_add_u32_e32 v37, 0xe00, v11
	v_lshl_add_u64 v[12:13], v[32:33], 2, v[8:9]
	v_mul_lo_u32 v32, v14, s56
	v_add_u32_e32 v16, s59, v56
	v_ashrrev_i32_e32 v55, 7, v37
	v_lshl_add_u64 v[14:15], v[32:33], 2, v[8:9]
	v_mul_lo_u32 v32, v16, s56
	v_add_u32_e32 v18, s59, v55
	v_lshl_add_u64 v[16:17], v[32:33], 2, v[8:9]
	v_mul_lo_u32 v32, v18, s56
	v_lshl_add_u64 v[18:19], v[32:33], 2, v[8:9]
	global_load_dword v21, v[0:1], off
	global_load_dword v22, v[2:3], off
	global_load_dword v24, v[4:5], off
	s_nop 0
	global_load_dword v6, v[6:7], off
	s_nop 0
	global_load_dword v7, v[12:13], off
	global_load_dword v26, v[14:15], off
	s_nop 0
	global_load_dword v16, v[16:17], off
	s_nop 0
	global_load_dword v17, v[18:19], off
	v_add_u32_e32 v0, 0x1000, v11
	v_ashrrev_i32_e32 v54, 7, v0
	v_add_u32_e32 v2, 0x1200, v11
	v_add_u32_e32 v0, s59, v54
	v_ashrrev_i32_e32 v53, 7, v2
	v_add_u32_e32 v4, 0x1400, v11
	v_mul_lo_u32 v32, v0, s56
	v_add_u32_e32 v2, s59, v53
	v_ashrrev_i32_e32 v52, 7, v4
	v_lshl_add_u64 v[0:1], v[32:33], 2, v[8:9]
	v_mul_lo_u32 v32, v2, s56
	v_add_u32_e32 v4, s59, v52
	v_lshl_add_u64 v[2:3], v[32:33], 2, v[8:9]
	v_mul_lo_u32 v32, v4, s56
	v_lshl_add_u64 v[4:5], v[32:33], 2, v[8:9]
	global_load_dword v28, v[0:1], off
	global_load_dword v30, v[2:3], off
	global_load_dword v34, v[4:5], off
	v_add_u32_e32 v0, 0x1600, v11
	v_add_u32_e32 v1, 0x1800, v11
	v_ashrrev_i32_e32 v51, 7, v0
	v_add_u32_e32 v2, 0x1a00, v11
	v_ashrrev_i32_e32 v50, 7, v1
	v_add_u32_e32 v0, s59, v51
	v_ashrrev_i32_e32 v49, 7, v2
	v_add_u32_e32 v1, s59, v50
	v_mul_lo_u32 v32, v0, s56
	v_lshl_add_u64 v[12:13], v[32:33], 2, v[8:9]
	v_mul_lo_u32 v32, v1, s56
	v_cmp_gt_u32_e32 vcc, s54, v10
	v_add_u32_e32 v10, s59, v49
	v_lshl_add_u64 v[14:15], v[32:33], 2, v[8:9]
	v_mul_lo_u32 v32, v10, s56
	v_add_u32_e32 v10, 0x1c00, v11
	v_ashrrev_i32_e32 v48, 7, v10
	v_add_u32_e32 v10, s59, v48
	v_mul_f32_e32 v36, 0x4f7ffffe, v36
	v_cvt_u32_f32_e32 v45, v36
	s_add_u32 s26, s4, s26
	s_addc_u32 s27, s5, s27
	v_ashrrev_i32_e32 v23, 5, v23
	v_ashrrev_i32_e32 v25, 5, v25
	v_ashrrev_i32_e32 v27, 5, v27
	v_ashrrev_i32_e32 v29, 5, v29
	v_ashrrev_i32_e32 v31, 5, v31
	v_ashrrev_i32_e32 v35, 5, v35
	v_ashrrev_i32_e32 v37, 5, v37
	v_mul_lo_u32 v65, v60, s82
	v_mul_lo_u32 v66, v59, s82
	v_mul_lo_u32 v67, v58, s82
	v_mul_lo_u32 v68, v57, s82
	v_mul_lo_u32 v69, v56, s82
	v_mul_lo_u32 v70, v55, s82
	v_mul_lo_u32 v71, v54, s82
	v_mul_lo_u32 v72, v53, s82
	v_mul_lo_u32 v73, v52, s82
	v_mul_lo_u32 v74, v51, s82
	v_mul_lo_u32 v75, v50, s82
	v_mul_lo_u32 v76, v49, s82
	v_mul_lo_u32 v77, v48, s82
	v_and_b32_e32 v40, 0x7f, v23
	v_and_b32_e32 v41, 0x7f, v25
	v_and_b32_e32 v42, 0x7f, v27
	v_and_b32_e32 v43, 0x7f, v29
	v_and_b32_e32 v44, 0x7f, v31
	v_and_b32_e32 v46, 0x7f, v35
	v_and_b32_e32 v63, 0x7f, v37
	s_waitcnt vmcnt(0)
; #define LAUNDER_V(x) asm volatile("" : "+v"(x))
; #define LAUNDER_S(x) asm volatile("" : "+s"(x))
;     float* tile = (float*)ldsb;
;     int tid = threadIdx.x; LAUNDER_V(tid); int bid = blockIdx.x; LAUNDER_S(bid);
;     const int nkt = K / 64, ntiles = (Ntot / 128) * nkt;
;     float v[16];
;     ...
;     const int cstride = nwg ? nwg : (int)gridDim.x; bid -= wg0;
;     if (bid < 0) return;
;     if (bid < ntiles) CONVW_LOAD(bid);
	v_cndmask_b32_e32 v0, 0, v21, vcc
	v_ashrrev_i32_e32 v21, 5, v11
	v_and_b32_e32 v39, 0x7f, v21
	v_cndmask_b32_e32 v3, 0, v6, vcc
	v_cndmask_b32_e32 v4, 0, v7, vcc
	v_cndmask_b32_e32 v1, 0, v22, vcc
	v_cndmask_b32_e32 v6, 0, v16, vcc
	v_cndmask_b32_e32 v7, 0, v17, vcc
	v_lshl_add_u64 v[16:17], v[32:33], 2, v[8:9]
	v_mul_lo_u32 v32, v10, s56
	v_add_u32_e32 v10, 0x1e00, v11
	v_ashrrev_i32_e32 v47, 7, v10
	v_add_u32_e32 v10, s59, v47
	v_lshl_add_u64 v[18:19], v[32:33], 2, v[8:9]
	v_mul_lo_u32 v32, v10, s56
	v_lshl_add_u64 v[8:9], v[32:33], 2, v[8:9]
	global_load_dword v12, v[12:13], off
	s_nop 0
	global_load_dword v13, v[14:15], off
	s_nop 0
	global_load_dword v14, v[16:17], off
	global_load_dword v15, v[18:19], off
	s_nop 0
	global_load_dword v18, v[8:9], off
	v_lshlrev_b32_e32 v16, 1, v11
	s_lshl_b32 s59, s58, 7
	v_and_b32_e32 v16, 62, v16
	s_cmp_lt_i32 s58, 0
	v_lshlrev_b32_e32 v32, 1, v16
	s_cselect_b64 s[4:5], -1, 0
	v_mad_u32_u24 v38, v16, s82, 0
	v_lshl_add_u64 v[16:17], s[28:29], 0, v[32:33]
	v_readfirstlane_b32 s28, v45
	s_sub_i32 s29, 0, s30
	s_mul_i32 s29, s29, s28
	s_mul_hi_u32 s29, s28, s29
	v_lshl_add_u32 v19, v20, 2, 0
	v_mul_lo_u32 v11, v62, s82
	v_mul_lo_u32 v32, v61, s82
	v_mul_lo_u32 v78, v47, s82
	s_add_i32 s58, s28, s29
	s_lshl_b32 s28, s30, 6
	s_lshl_b32 s69, s34, 6
	v_cndmask_b32_e32 v2, 0, v24, vcc
	v_cndmask_b32_e32 v5, 0, v26, vcc
	v_cndmask_b32_e32 v8, 0, v28, vcc
	v_cndmask_b32_e32 v9, 0, v30, vcc
	v_cndmask_b32_e32 v10, 0, v34, vcc
	v_lshl_add_u32 v22, v21, 2, v38
	v_lshl_add_u32 v24, v23, 2, v38
	v_lshl_add_u32 v26, v25, 2, v38
	v_lshl_add_u32 v28, v27, 2, v38
	v_lshl_add_u32 v30, v29, 2, v38
	v_lshl_add_u32 v34, v31, 2, v38
	v_lshl_add_u32 v36, v35, 2, v38
	v_lshl_add_u32 v38, v37, 2, v38
	v_or_b32_e32 v39, s59, v39
	v_or_b32_e32 v40, s59, v40
	v_or_b32_e32 v41, s59, v41
	v_or_b32_e32 v42, s59, v42
	v_or_b32_e32 v43, s59, v43
	v_or_b32_e32 v44, s59, v44
	v_or_b32_e32 v45, s59, v46
	v_or_b32_e32 v46, s59, v63
	s_sub_i32 s59, 0, s28
	s_lshl_b32 s68, s70, 6
	v_add_u32_e32 v47, s69, v47
	v_add_u32_e32 v48, s69, v48
	v_add_u32_e32 v49, s69, v49
	v_add_u32_e32 v50, s69, v50
	v_add_u32_e32 v51, s69, v51
	v_add_u32_e32 v52, s69, v52
	v_add_u32_e32 v53, s69, v53
	v_add_u32_e32 v54, s69, v54
	v_add_u32_e32 v55, s69, v55
	v_add_u32_e32 v56, s69, v56
	v_add_u32_e32 v57, s69, v57
	v_add_u32_e32 v58, s69, v58
	v_add_u32_e32 v59, s69, v59
	v_add_u32_e32 v60, s69, v60
	v_add_u32_e32 v61, s69, v61
	v_add_u32_e32 v62, s69, v62
	v_add_u32_e32 v63, v19, v11
	v_add_u32_e32 v64, v19, v32
	v_add_u32_e32 v65, v19, v65
	v_add_u32_e32 v66, v19, v66
	v_add_u32_e32 v67, v19, v67
	v_add_u32_e32 v68, v19, v68
	v_add_u32_e32 v69, v19, v69
	v_add_u32_e32 v70, v19, v70
	v_add_u32_e32 v71, v19, v71
	v_add_u32_e32 v72, v19, v72
	v_add_u32_e32 v73, v19, v73
	v_add_u32_e32 v74, v19, v74
	v_add_u32_e32 v75, v19, v75
	v_add_u32_e32 v76, v19, v76
	v_add_u32_e32 v77, v19, v77
	v_add_u32_e32 v78, v19, v78
	s_waitcnt vmcnt(0)
	v_cndmask_b32_e32 v11, 0, v12, vcc
	v_cndmask_b32_e32 v12, 0, v13, vcc
	v_cndmask_b32_e32 v13, 0, v14, vcc
	v_cndmask_b32_e32 v14, 0, v15, vcc
	v_cndmask_b32_e32 v15, 0, v18, vcc
	s_mov_b64 s[98:99], -1
	s_nop 1
	s_branch .LBB0_843

; #define LDS_BARRIER() do { asm volatile("s_waitcnt lgkmcnt(0)" ::: "memory"); __builtin_amdgcn_s_barrier(); asm volatile("" ::: "memory"); } while (0)
;     ...
;     const int cstride = nwg ? nwg : (int)gridDim.x; bid -= wg0;
;     if (bid < 0) return;
;     if (bid < ntiles) CONVW_LOAD(bid);
;     for (int t = bid; t < ntiles; t += cstride) {
;         const int n0 = (t / nkt) * 128, k0 = (t % nkt) * 64;
; #pragma unroll
;         for (int it = 0; it < 16; ++it) { const int e = tid + 512 * it, kk = e >> 7, nn = e & 127; tile[kk * 129 + nn] = v[it]; }
;         LDS_BARRIER();
;         if (t + cstride < ntiles) CONVW_LOAD(t + cstride);
.LBB0_843:
	s_waitcnt vmcnt(8)
	v_cndmask_b32_e64 v0, 0, v0, s[98:99]
	v_cndmask_b32_e64 v1, 0, v1, s[98:99]
	v_cndmask_b32_e64 v2, 0, v2, s[98:99]
	v_cndmask_b32_e64 v3, 0, v3, s[98:99]
	v_cndmask_b32_e64 v4, 0, v4, s[98:99]
	v_cndmask_b32_e64 v5, 0, v5, s[98:99]
	v_cndmask_b32_e64 v6, 0, v6, s[98:99]
	v_cndmask_b32_e64 v7, 0, v7, s[98:99]
	v_cndmask_b32_e64 v8, 0, v8, s[98:99]
	v_cndmask_b32_e64 v9, 0, v9, s[98:99]
	v_cndmask_b32_e64 v10, 0, v10, s[98:99]
	v_cndmask_b32_e64 v11, 0, v11, s[98:99]
	v_cndmask_b32_e64 v12, 0, v12, s[98:99]
	v_cndmask_b32_e64 v13, 0, v13, s[98:99]
	v_cndmask_b32_e64 v14, 0, v14, s[98:99]
	v_cndmask_b32_e64 v15, 0, v15, s[98:99]
	ds_write_b32 v63, v0
	ds_write_b32 v64, v1
	ds_write_b32 v65, v2
	ds_write_b32 v66, v3
	ds_write_b32 v67, v4
	ds_write_b32 v68, v5
	ds_write_b32 v69, v6
	ds_write_b32 v70, v7
	ds_write_b32 v71, v8
	ds_write_b32 v72, v9
	ds_write_b32 v73, v10
	ds_write_b32 v74, v11
	ds_write_b32 v75, v12
	ds_write_b32 v76, v13
	ds_write_b32 v77, v14
	ds_write_b32 v78, v15
	s_add_i32 s71, s70, s34
	s_waitcnt lgkmcnt(0)
	s_barrier
	s_cmp_ge_i32 s71, s31
	s_cselect_b64 s[28:29], -1, 0
	s_and_b64 vcc, exec, s[28:29]
	s_cbranch_vccnz .LBB0_842
	s_abs_i32 s73, s71
	s_mul_hi_u32 s75, s73, s58
	s_mul_i32 s76, s75, s30
	s_sub_i32 s73, s73, s76
	s_ashr_i32 s72, s71, 31
	s_add_i32 s76, s75, 1
	s_sub_i32 s77, s73, s30
	s_cmp_ge_u32 s73, s30
	s_cselect_b32 s75, s76, s75
	s_cselect_b32 s73, s77, s73
	s_add_i32 s76, s75, 1
	s_cmp_ge_u32 s73, s30
	s_cselect_b32 s73, s76, s75
	s_xor_b32 s73, s73, s72
	s_sub_i32 s72, s73, s72
	v_lshl_or_b32 v0, s72, 7, v20
	v_cmp_gt_i32_e32 vcc, s54, v0
	v_min_i32_e32 v0, s57, v0
	s_mul_i32 s72, s59, s72
	v_ashrrev_i32_e32 v1, 31, v0
	s_add_i32 s72, s72, s68
	v_lshl_add_u64 v[18:19], v[0:1], 2, s[26:27]
	v_add_u32_e32 v0, s72, v62
	v_mul_lo_u32 v32, v0, s56
	v_lshl_add_u64 v[0:1], v[32:33], 2, v[18:19]
	global_load_dword v0, v[0:1], off
	v_add_u32_e32 v1, s72, v61
	v_mul_lo_u32 v32, v1, s56
	v_lshl_add_u64 v[2:3], v[32:33], 2, v[18:19]
	global_load_dword v1, v[2:3], off
	v_add_u32_e32 v2, s72, v60
	v_mul_lo_u32 v32, v2, s56
	v_lshl_add_u64 v[2:3], v[32:33], 2, v[18:19]
	global_load_dword v2, v[2:3], off
	v_add_u32_e32 v3, s72, v59
	v_mul_lo_u32 v32, v3, s56
	v_lshl_add_u64 v[4:5], v[32:33], 2, v[18:19]
	global_load_dword v3, v[4:5], off
	v_add_u32_e32 v4, s72, v58
	v_mul_lo_u32 v32, v4, s56
	v_lshl_add_u64 v[4:5], v[32:33], 2, v[18:19]
	global_load_dword v4, v[4:5], off
	v_add_u32_e32 v5, s72, v57
	v_mul_lo_u32 v32, v5, s56
	v_lshl_add_u64 v[6:7], v[32:33], 2, v[18:19]
	global_load_dword v5, v[6:7], off
	v_add_u32_e32 v6, s72, v56
	v_mul_lo_u32 v32, v6, s56
	v_lshl_add_u64 v[6:7], v[32:33], 2, v[18:19]
	global_load_dword v6, v[6:7], off
	v_add_u32_e32 v7, s72, v55
	v_mul_lo_u32 v32, v7, s56
	v_lshl_add_u64 v[8:9], v[32:33], 2, v[18:19]
	global_load_dword v7, v[8:9], off
	v_add_u32_e32 v8, s72, v54
	v_mul_lo_u32 v32, v8, s56
	v_lshl_add_u64 v[8:9], v[32:33], 2, v[18:19]
	global_load_dword v8, v[8:9], off
	v_add_u32_e32 v9, s72, v53
	v_mul_lo_u32 v32, v9, s56
	v_lshl_add_u64 v[10:11], v[32:33], 2, v[18:19]
	global_load_dword v9, v[10:11], off
	v_add_u32_e32 v10, s72, v52
	v_mul_lo_u32 v32, v10, s56
	v_lshl_add_u64 v[10:11], v[32:33], 2, v[18:19]
	global_load_dword v10, v[10:11], off
	v_add_u32_e32 v11, s72, v51
	v_mul_lo_u32 v32, v11, s56
	v_lshl_add_u64 v[12:13], v[32:33], 2, v[18:19]
	global_load_dword v11, v[12:13], off
	v_add_u32_e32 v12, s72, v50
	v_mul_lo_u32 v32, v12, s56
	v_lshl_add_u64 v[12:13], v[32:33], 2, v[18:19]
	global_load_dword v12, v[12:13], off
	v_add_u32_e32 v13, s72, v49
	v_mul_lo_u32 v32, v13, s56
	v_lshl_add_u64 v[14:15], v[32:33], 2, v[18:19]
	global_load_dword v13, v[14:15], off
	v_add_u32_e32 v14, s72, v48
	v_mul_lo_u32 v32, v14, s56
	v_lshl_add_u64 v[14:15], v[32:33], 2, v[18:19]
	global_load_dword v14, v[14:15], off
	v_add_u32_e32 v15, s72, v47
	v_mul_lo_u32 v32, v15, s56
	v_lshl_add_u64 v[18:19], v[32:33], 2, v[18:19]
	global_load_dword v15, v[18:19], off
	s_mov_b64 s[98:99], vcc
	s_branch .LBB0_842
